# leading half's align barrier moved to just before the epilogue's first vmcnt(0) wait
# speedup vs baseline: 1.0070x; 1.0028x over previous
; __device__ __forceinline__ unsigned cvt_pk_bf16(float lo, float hi) { unsigned r; asm volatile("v_cvt_pk_bf16_f32 %0, %1, %2" : "=v"(r) : "v"(lo), "v"(hi)); return r; }
; #define PG8_BAR __builtin_amdgcn_s_barrier()
;     __device__ __forceinline__ void operator()(f32x4 (&acc)[2][2][4][2], const Unit& u, int wr, int wc, int fr, int fq) const {
;         const int row0 = u.pm * BM + wr * 64 + fr, col0 = u.pn * HALF + wc * 32 + 8 * fq;
;         bf16_t* Ob = O + ((size_t)(u.pm * ldc + (col0 >> 6)) * BM) * 64;
;         float sq[2][4];
; #pragma unroll
;         for (int ai = 0; ai < 2; ++ai)
; #pragma unroll
;             for (int m = 0; m < 4; ++m) sq[ai][m] = ssq[row0 + ai * HALF + m * 16];
; #pragma unroll
;         for (int ai = 0; ai < 2; ++ai)
; #pragma unroll
;             for (int m = 0; m < 4; ++m) { const float ms = sq[ai][m] * (1.0f / 1024.0f) + 1e-6f, nrl = -__builtin_amdgcn_rsqf(ms) * LOG2E;
;                 float o[8];
; #pragma unroll
;                 for (int n = 0; n < 2; ++n)
; #pragma unroll
;                     for (int e = 0; e < 4; ++e) { const float a = acc[ai][0][m][n][e], bb = acc[ai][1][m][n][e];
;                         o[4 * n + e] = (a * bb) * __builtin_amdgcn_rcpf(__builtin_fmaf(__builtin_amdgcn_exp2f(a * nrl), ms, ms)); }
;                 u32x4 w; w.x = cvt_pk_bf16(o[0], o[1]); w.y = cvt_pk_bf16(o[2], o[3]); w.z = cvt_pk_bf16(o[4], o[5]); w.w = cvt_pk_bf16(o[6], o[7]);
; template <class Epi, class Sched, bool ALIGN_EPI = false, bool SP2 = false>
; __device__ __forceinline__ void gemm_phase(PG8_LAS unsigned char* lds, const Gemm g, const Sched& S, const Epi& E) {
;     ...
;         if constexpr (ALIGN_EPI) { if (wr == 0) PG8_BAR; }
.LBB0_144:
	v_lshl_add_u32 v150, s68, 8, v142
	v_ashrrev_i32_e32 v151, 31, v150
	v_lshl_add_u64 v[150:151], v[150:151], 2, s[22:23]
	global_load_dword v149, v[150:151], off
	global_load_dword v152, v[150:151], off offset:64
	v_mul_f32_e32 v155, v108, v104
	global_load_dword v156, v[150:151], off offset:128
	global_load_dword v157, v[150:151], off offset:192
	global_load_dword v158, v[150:151], off offset:512
	global_load_dword v159, v[150:151], off offset:576
	global_load_dword v160, v[150:151], off offset:640
	global_load_dword v104, v[150:151], off offset:704
	v_mul_f32_e32 v105, v109, v105
	v_mul_f32_e32 v106, v110, v106
	v_mul_f32_e32 v96, v100, v96
	v_mul_f32_e32 v124, v116, v124
	v_mul_f32_e32 v125, v117, v125
	v_mul_f32_e32 v126, v118, v126
	v_mul_f32_e32 v127, v119, v127
	v_mul_f32_e32 v153, v112, v120
	v_mul_f32_e32 v154, v113, v121
	v_mul_f32_e32 v122, v114, v122
	v_mul_f32_e32 v123, v115, v123
	s_lshl_b32 s8, s69, 7
	s_or_b32 s8, s8, s79
	s_mul_i32 s9, s68, 44
	s_ashr_i32 s8, s8, 6
	s_add_i32 s8, s8, s9
	v_mul_f32_e32 v98, v102, v98
	s_ashr_i32 s9, s8, 31
	s_lshl_b64 s[8:9], s[8:9], 15
	s_add_u32 s68, s28, s8
	s_addc_u32 s69, s29, s9
	v_lshl_add_u64 v[120:121], s[68:69], 0, v[130:131]
	v_mul_f32_e32 v107, v111, v107
	v_mul_f32_e32 v88, v92, v88
	v_mul_f32_e32 v89, v93, v89
	v_mul_f32_e32 v90, v94, v90
	v_mul_f32_e32 v91, v95, v91
	v_mul_f32_e32 v80, v84, v80
	v_mul_f32_e32 v82, v86, v82
	v_mul_f32_e32 v72, v76, v72
	v_mul_f32_e32 v73, v77, v73
	v_mul_f32_e32 v74, v78, v74
	v_mul_f32_e32 v75, v79, v75
	v_mul_f32_e32 v64, v68, v64
	v_mul_f32_e32 v66, v70, v66
	v_mul_f32_e32 v56, v60, v56
	v_mul_f32_e32 v57, v61, v57
	v_mul_f32_e32 v58, v62, v58
	v_mul_f32_e32 v59, v63, v59
	v_mul_f32_e32 v48, v52, v48
	v_mul_f32_e32 v50, v54, v50
	v_mul_f32_e32 v40, v44, v40
	v_mul_f32_e32 v41, v45, v41
	v_mul_f32_e32 v42, v46, v42
	v_mul_f32_e32 v43, v47, v43
	v_mul_f32_e32 v32, v36, v32
	v_mul_f32_e32 v34, v38, v34
	v_mul_f32_e32 v24, v28, v24
	v_mul_f32_e32 v25, v29, v25
	v_mul_f32_e32 v26, v30, v26
	v_mul_f32_e32 v27, v31, v27
	v_mul_f32_e32 v16, v20, v16
	v_mul_f32_e32 v18, v22, v18
	v_mul_f32_e32 v8, v12, v8
	v_mul_f32_e32 v9, v13, v9
	v_mul_f32_e32 v10, v14, v10
	v_mul_f32_e32 v11, v15, v11
	v_mul_f32_e32 v0, v4, v0
	v_mul_f32_e32 v2, v6, v2
	v_readlane_b32 s99, v246, 6
	s_nop 1
	s_cmp_lt_u32 s99, 4
	s_cbranch_scc0 .Lnoal_0
	s_barrier
.Lnoal_0:
	s_waitcnt vmcnt(0)
	v_fmamk_f32 v149, v149, 0x3a800000, v148
	v_fmamk_f32 v150, v152, 0x3a800000, v148
	v_rsq_f32_e32 v152, v150
	v_rsq_f32_e32 v151, v149
	v_mul_f32_e32 v152, 0xbfb8aa3b, v152
	v_mul_f32_e32 v109, v109, v152
	v_exp_f32_e32 v109, v109
	v_mul_f32_e32 v110, v110, v152
	v_exp_f32_e32 v110, v110
	v_mul_f32_e32 v161, v100, v152
	v_fma_f32 v109, v109, v150, v150
	v_rcp_f32_e32 v109, v109
	v_fma_f32 v110, v110, v150, v150
	v_rcp_f32_e32 v110, v110
	v_mul_f32_e32 v151, 0xbfb8aa3b, v151
	v_mul_f32_e32 v105, v105, v109
	v_exp_f32_e32 v109, v161
	v_mul_f32_e32 v106, v106, v110
	v_mul_f32_e32 v110, v101, v152
	v_exp_f32_e32 v110, v110
	v_fma_f32 v109, v109, v150, v150
	v_rcp_f32_e32 v109, v109
	v_mul_f32_e32 v116, v116, v151
	v_mul_f32_e32 v117, v117, v151
	v_mul_f32_e32 v118, v118, v151
	v_mul_f32_e32 v100, v96, v109
	v_mul_f32_e32 v96, v101, v97
	v_fma_f32 v97, v110, v150, v150
	v_mul_f32_e32 v101, v102, v152
	v_rcp_f32_e32 v97, v97
	v_exp_f32_e32 v101, v101
	v_mul_f32_e32 v119, v119, v151
	v_mul_f32_e32 v112, v112, v151
	v_mul_f32_e32 v113, v113, v151
	v_mul_f32_e32 v114, v114, v151
	v_mul_f32_e32 v115, v115, v151
	v_mul_f32_e32 v108, v108, v152
	v_mul_f32_e32 v151, v111, v152
	v_exp_f32_e32 v116, v116
	v_mul_f32_e32 v109, v103, v152
	v_mul_f32_e32 v110, v96, v97
	v_fma_f32 v96, v101, v150, v150
	v_exp_f32_e32 v117, v117
	v_exp_f32_e32 v118, v118
	v_exp_f32_e32 v119, v119
	v_exp_f32_e32 v112, v112
	v_exp_f32_e32 v113, v113
	v_exp_f32_e32 v114, v114
	v_exp_f32_e32 v115, v115
	v_exp_f32_e32 v108, v108
	v_exp_f32_e32 v151, v151
	v_exp_f32_e32 v109, v109
	v_rcp_f32_e32 v96, v96
	v_fma_f32 v116, v116, v149, v149
	v_fmamk_f32 v102, v156, 0x3a800000, v148
	v_fma_f32 v117, v117, v149, v149
	v_fma_f32 v118, v118, v149, v149
	v_fma_f32 v119, v119, v149, v149
	v_fma_f32 v112, v112, v149, v149
	v_fma_f32 v113, v113, v149, v149
	v_fma_f32 v114, v114, v149, v149
	v_fmac_f32_e32 v149, v115, v149
	v_fma_f32 v108, v108, v150, v150
	v_fma_f32 v115, v151, v150, v150
	v_rcp_f32_e32 v116, v116
	v_fmac_f32_e32 v150, v109, v150
	v_mul_f32_e32 v101, v98, v96
	v_mul_f32_e32 v96, v103, v99
	v_rsq_f32_e32 v103, v102
	v_rcp_f32_e32 v117, v117
	v_rcp_f32_e32 v118, v118
	v_rcp_f32_e32 v119, v119
	v_rcp_f32_e32 v112, v112
	v_rcp_f32_e32 v113, v113
	v_rcp_f32_e32 v114, v114
	v_rcp_f32_e32 v149, v149
	v_rcp_f32_e32 v108, v108
	v_rcp_f32_e32 v151, v115
	v_rcp_f32_e32 v97, v150
	v_mul_f32_e32 v115, v124, v116
	v_mul_f32_e32 v103, 0xbfb8aa3b, v103
	v_mul_f32_e32 v116, v125, v117
	v_mul_f32_e32 v117, v126, v118
	v_mul_f32_e32 v118, v127, v119
	v_mul_f32_e32 v119, v153, v112
	v_mul_f32_e32 v124, v154, v113
	v_mul_f32_e32 v122, v122, v114
	v_mul_f32_e32 v123, v123, v149
	v_mul_f32_e32 v108, v155, v108
	v_cvt_pk_bf16_f32 v112, v115, v116
	v_cvt_pk_bf16_f32 v113, v117, v118
	v_cvt_pk_bf16_f32 v114, v119, v124
	v_cvt_pk_bf16_f32 v115, v122, v123
	global_store_dwordx4 v[120:121], v[112:115], off sc1
	v_mul_f32_e32 v107, v107, v151
	v_mul_f32_e32 v99, v96, v97
	v_cvt_pk_bf16_f32 v96, v108, v105
	v_cvt_pk_bf16_f32 v97, v106, v107
	v_mul_f32_e32 v105, v92, v103
	v_mul_f32_e32 v106, v93, v103
	v_mul_f32_e32 v92, v94, v103
	v_mul_f32_e32 v93, v95, v103
	v_exp_f32_e32 v92, v92
	v_exp_f32_e32 v93, v93
	v_mul_f32_e32 v94, v84, v103
; __device__ __forceinline__ unsigned cvt_pk_bf16(float lo, float hi) { unsigned r; asm volatile("v_cvt_pk_bf16_f32 %0, %1, %2" : "=v"(r) : "v"(lo), "v"(hi)); return r; }
;     __device__ __forceinline__ void operator()(f32x4 (&acc)[2][2][4][2], const Unit& u, int wr, int wc, int fr, int fq) const {
;     ...
;             for (int m = 0; m < 4; ++m) { const float ms = sq[ai][m] * (1.0f / 1024.0f) + 1e-6f, nrl = -__builtin_amdgcn_rsqf(ms) * LOG2E;
;                 float o[8];
; #pragma unroll
;                 for (int n = 0; n < 2; ++n)
; #pragma unroll
;                     for (int e = 0; e < 4; ++e) { const float a = acc[ai][0][m][n][e], bb = acc[ai][1][m][n][e];
;                         o[4 * n + e] = (a * bb) * __builtin_amdgcn_rcpf(__builtin_fmaf(__builtin_amdgcn_exp2f(a * nrl), ms, ms)); }
;                 u32x4 w; w.x = cvt_pk_bf16(o[0], o[1]); w.y = cvt_pk_bf16(o[2], o[3]); w.z = cvt_pk_bf16(o[4], o[5]); w.w = cvt_pk_bf16(o[6], o[7]);
;                 *(u32x4*)((char*)Ob + ai * HTB + lds_byte(wr * 64 + m * 16 + fr, (col0 & 63))) = w; }
	v_exp_f32_e32 v94, v94
	v_fma_f32 v92, v92, v102, v102
	v_fma_f32 v93, v93, v102, v102
	v_rcp_f32_e32 v92, v92
	v_rcp_f32_e32 v93, v93
	v_exp_f32_e32 v105, v105
	v_exp_f32_e32 v106, v106
	v_mul_f32_e32 v90, v90, v92
	v_mul_f32_e32 v91, v91, v93
	v_fma_f32 v92, v94, v102, v102
	v_mul_f32_e32 v93, v85, v103
	v_rcp_f32_e32 v92, v92
	v_exp_f32_e32 v93, v93
	v_cvt_pk_bf16_f32 v98, v100, v110
	v_cvt_pk_bf16_f32 v99, v101, v99
	v_mul_f32_e32 v84, v80, v92
	v_mul_f32_e32 v80, v85, v81
	v_fma_f32 v81, v93, v102, v102
	v_mul_f32_e32 v85, v86, v103
	v_rcp_f32_e32 v81, v81
	v_exp_f32_e32 v85, v85
	v_mul_f32_e32 v92, v87, v103
	v_exp_f32_e32 v92, v92
	v_mul_f32_e32 v93, v80, v81
	v_fma_f32 v80, v85, v102, v102
	v_rcp_f32_e32 v80, v80
	v_lshl_add_u64 v[100:101], s[68:69], 0, v[132:133]
	global_store_dwordx4 v[100:101], v[96:99], off sc1
	v_fmamk_f32 v86, v157, 0x3a800000, v148
	v_mul_f32_e32 v85, v82, v80
	v_fma_f32 v96, v105, v102, v102
	v_fma_f32 v97, v106, v102, v102
	v_rcp_f32_e32 v96, v96
	v_rcp_f32_e32 v97, v97
	v_fmac_f32_e32 v102, v92, v102
	v_mul_f32_e32 v80, v87, v83
	v_rsq_f32_e32 v87, v86
	v_rcp_f32_e32 v81, v102
	v_mul_f32_e32 v88, v88, v96
	v_mul_f32_e32 v89, v89, v97
	v_mul_f32_e32 v87, 0xbfb8aa3b, v87
	v_mul_f32_e32 v83, v80, v81
	v_cvt_pk_bf16_f32 v80, v88, v89
	v_mul_f32_e32 v88, v76, v87
	v_mul_f32_e32 v89, v77, v87
	v_mul_f32_e32 v76, v78, v87
	v_mul_f32_e32 v77, v79, v87
	v_exp_f32_e32 v76, v76
	v_exp_f32_e32 v77, v77
	v_mul_f32_e32 v78, v68, v87
	v_exp_f32_e32 v78, v78
	v_fma_f32 v76, v76, v86, v86
	v_fma_f32 v77, v77, v86, v86
	v_rcp_f32_e32 v76, v76
	v_rcp_f32_e32 v77, v77
	v_exp_f32_e32 v88, v88
	v_exp_f32_e32 v89, v89
	v_mul_f32_e32 v74, v74, v76
	v_mul_f32_e32 v75, v75, v77
	v_fma_f32 v76, v78, v86, v86
	v_mul_f32_e32 v77, v69, v87
	v_rcp_f32_e32 v76, v76
	v_exp_f32_e32 v77, v77
	v_cvt_pk_bf16_f32 v81, v90, v91
	v_cvt_pk_bf16_f32 v82, v84, v93
	v_mul_f32_e32 v68, v64, v76
	v_mul_f32_e32 v64, v69, v65
	v_fma_f32 v65, v77, v86, v86
	v_mul_f32_e32 v69, v70, v87
	v_rcp_f32_e32 v65, v65
	v_exp_f32_e32 v69, v69
	v_mul_f32_e32 v76, v71, v87
	v_exp_f32_e32 v76, v76
	v_mul_f32_e32 v77, v64, v65
	v_fma_f32 v64, v69, v86, v86
	v_cvt_pk_bf16_f32 v83, v85, v83
	v_lshl_add_u64 v[84:85], s[68:69], 0, v[134:135]
	v_rcp_f32_e32 v64, v64
	global_store_dwordx4 v[84:85], v[80:83], off sc1
	v_fmamk_f32 v70, v158, 0x3a800000, v148
	v_mul_f32_e32 v69, v66, v64
	v_fma_f32 v80, v88, v86, v86
	v_fma_f32 v81, v89, v86, v86
	v_fmac_f32_e32 v86, v76, v86
	v_rcp_f32_e32 v65, v86
	v_rcp_f32_e32 v80, v80
	v_rcp_f32_e32 v81, v81
	v_mul_f32_e32 v64, v71, v67
	v_rsq_f32_e32 v71, v70
	v_mul_f32_e32 v67, v64, v65
	v_mul_f32_e32 v72, v72, v80
	v_mul_f32_e32 v73, v73, v81
	v_cvt_pk_bf16_f32 v64, v72, v73
	v_cvt_pk_bf16_f32 v65, v74, v75
	v_cvt_pk_bf16_f32 v66, v68, v77
	v_cvt_pk_bf16_f32 v67, v69, v67
	v_lshl_add_u64 v[68:69], s[68:69], 0, v[136:137]
	global_store_dwordx4 v[68:69], v[64:67], off sc1
	s_add_u32 s68, s68, 0x4000
	s_addc_u32 s69, s69, 0
	v_mul_f32_e32 v64, 0xbfb8aa3b, v71
	v_mul_f32_e32 v65, v60, v64
	v_mul_f32_e32 v66, v61, v64
	v_mul_f32_e32 v60, v62, v64
	v_mul_f32_e32 v61, v63, v64
	v_exp_f32_e32 v60, v60
	v_exp_f32_e32 v61, v61
	v_mul_f32_e32 v62, v52, v64
	v_exp_f32_e32 v62, v62
	v_fma_f32 v60, v60, v70, v70
	v_fma_f32 v61, v61, v70, v70
	v_rcp_f32_e32 v60, v60
	v_rcp_f32_e32 v61, v61
	v_exp_f32_e32 v65, v65
	v_exp_f32_e32 v66, v66
	v_mul_f32_e32 v58, v58, v60
	v_mul_f32_e32 v59, v59, v61
	v_fma_f32 v60, v62, v70, v70
	v_mul_f32_e32 v61, v53, v64
	v_rcp_f32_e32 v60, v60
	v_exp_f32_e32 v61, v61
	v_fma_f32 v65, v65, v70, v70
	v_fma_f32 v66, v66, v70, v70
	v_mul_f32_e32 v52, v48, v60
	v_mul_f32_e32 v48, v53, v49
	v_fma_f32 v49, v61, v70, v70
	v_mul_f32_e32 v53, v54, v64
	v_rcp_f32_e32 v49, v49
	v_exp_f32_e32 v53, v53
	v_mul_f32_e32 v60, v55, v64
	v_exp_f32_e32 v60, v60
	v_mul_f32_e32 v61, v48, v49
	v_fma_f32 v48, v53, v70, v70
	v_rcp_f32_e32 v48, v48
	v_fmamk_f32 v54, v159, 0x3a800000, v148
	v_rcp_f32_e32 v65, v65
	v_rcp_f32_e32 v66, v66
	v_fmac_f32_e32 v70, v60, v70
	v_mul_f32_e32 v53, v50, v48
	v_mul_f32_e32 v48, v55, v51
	v_rsq_f32_e32 v55, v54
	v_rcp_f32_e32 v49, v70
	v_mul_f32_e32 v56, v56, v65
	v_mul_f32_e32 v57, v57, v66
	v_mul_f32_e32 v55, 0xbfb8aa3b, v55
	v_mul_f32_e32 v51, v48, v49
	v_cvt_pk_bf16_f32 v48, v56, v57
	v_mul_f32_e32 v56, v44, v55
	v_mul_f32_e32 v57, v45, v55
	v_mul_f32_e32 v44, v46, v55
	v_mul_f32_e32 v45, v47, v55
	v_exp_f32_e32 v44, v44
	v_exp_f32_e32 v45, v45
	v_mul_f32_e32 v46, v36, v55
; __device__ __forceinline__ unsigned cvt_pk_bf16(float lo, float hi) { unsigned r; asm volatile("v_cvt_pk_bf16_f32 %0, %1, %2" : "=v"(r) : "v"(lo), "v"(hi)); return r; }
; #define PG8_BAR __builtin_amdgcn_s_barrier()
;     __device__ __forceinline__ void operator()(f32x4 (&acc)[2][2][4][2], const Unit& u, int wr, int wc, int fr, int fq) const {
;     ...
;             for (int m = 0; m < 4; ++m) { const float ms = sq[ai][m] * (1.0f / 1024.0f) + 1e-6f, nrl = -__builtin_amdgcn_rsqf(ms) * LOG2E;
;                 float o[8];
; #pragma unroll
;                 for (int n = 0; n < 2; ++n)
; #pragma unroll
;                     for (int e = 0; e < 4; ++e) { const float a = acc[ai][0][m][n][e], bb = acc[ai][1][m][n][e];
;                         o[4 * n + e] = (a * bb) * __builtin_amdgcn_rcpf(__builtin_fmaf(__builtin_amdgcn_exp2f(a * nrl), ms, ms)); }
;                 u32x4 w; w.x = cvt_pk_bf16(o[0], o[1]); w.y = cvt_pk_bf16(o[2], o[3]); w.z = cvt_pk_bf16(o[4], o[5]); w.w = cvt_pk_bf16(o[6], o[7]);
;                 *(u32x4*)((char*)Ob + ai * HTB + lds_byte(wr * 64 + m * 16 + fr, (col0 & 63))) = w; }
; template <class Epi, class Sched, bool ALIGN_EPI = false, bool SP2 = false>
; __device__ __forceinline__ void gemm_phase(PG8_LAS unsigned char* lds, const Gemm g, const Sched& S, const Epi& E) {
;     ...
;         if (!has_next) break;
; #pragma unroll
;         for (int a = 0; a < 2; ++a)
; #pragma unroll
;             for (int b = 0; b < 2; ++b)
; #pragma unroll
;                 for (int m = 0; m < 4; ++m)
; #pragma unroll
;                     for (int n = 0; n < 2; ++n) acc[a][b][m][n] = (f32x4){0.f, 0.f, 0.f, 0.f};
;         cur = nxt; cA = nA; cB = nB; ++ui;
;         if constexpr (ALIGN_EPI) { if (wr == 1) PG8_BAR; }
	v_exp_f32_e32 v46, v46
	v_fma_f32 v44, v44, v54, v54
	v_fma_f32 v45, v45, v54, v54
	v_rcp_f32_e32 v44, v44
	v_rcp_f32_e32 v45, v45
	v_exp_f32_e32 v56, v56
	v_exp_f32_e32 v57, v57
	v_mul_f32_e32 v42, v42, v44
	v_mul_f32_e32 v43, v43, v45
	v_fma_f32 v44, v46, v54, v54
	v_mul_f32_e32 v45, v37, v55
	v_rcp_f32_e32 v44, v44
	v_exp_f32_e32 v45, v45
	v_cvt_pk_bf16_f32 v49, v58, v59
	v_cvt_pk_bf16_f32 v50, v52, v61
	v_mul_f32_e32 v36, v32, v44
	v_mul_f32_e32 v32, v37, v33
	v_fma_f32 v33, v45, v54, v54
	v_mul_f32_e32 v37, v38, v55
	v_rcp_f32_e32 v33, v33
	v_exp_f32_e32 v37, v37
	v_mul_f32_e32 v44, v39, v55
	v_exp_f32_e32 v44, v44
	v_mul_f32_e32 v45, v32, v33
	v_fma_f32 v32, v37, v54, v54
	v_rcp_f32_e32 v32, v32
	v_cvt_pk_bf16_f32 v51, v53, v51
	v_lshl_add_u64 v[52:53], s[68:69], 0, v[130:131]
	global_store_dwordx4 v[52:53], v[48:51], off sc1
	v_fmamk_f32 v38, v160, 0x3a800000, v148
	v_mul_f32_e32 v37, v34, v32
	v_fma_f32 v48, v56, v54, v54
	v_fma_f32 v49, v57, v54, v54
	v_rcp_f32_e32 v48, v48
	v_rcp_f32_e32 v49, v49
	v_fmac_f32_e32 v54, v44, v54
	v_mul_f32_e32 v32, v39, v35
	v_rsq_f32_e32 v39, v38
	v_rcp_f32_e32 v33, v54
	v_mul_f32_e32 v40, v40, v48
	v_mul_f32_e32 v41, v41, v49
	v_mul_f32_e32 v39, 0xbfb8aa3b, v39
	v_mul_f32_e32 v35, v32, v33
	v_cvt_pk_bf16_f32 v32, v40, v41
	v_mul_f32_e32 v40, v28, v39
	v_mul_f32_e32 v41, v29, v39
	v_mul_f32_e32 v28, v30, v39
	v_mul_f32_e32 v29, v31, v39
	v_exp_f32_e32 v28, v28
	v_exp_f32_e32 v29, v29
	v_mul_f32_e32 v30, v20, v39
	v_exp_f32_e32 v30, v30
	v_fma_f32 v28, v28, v38, v38
	v_fma_f32 v29, v29, v38, v38
	v_rcp_f32_e32 v28, v28
	v_rcp_f32_e32 v29, v29
	v_exp_f32_e32 v40, v40
	v_exp_f32_e32 v41, v41
	v_mul_f32_e32 v26, v26, v28
	v_mul_f32_e32 v27, v27, v29
	v_fma_f32 v28, v30, v38, v38
	v_mul_f32_e32 v29, v21, v39
	v_rcp_f32_e32 v28, v28
	v_exp_f32_e32 v29, v29
	v_cvt_pk_bf16_f32 v33, v42, v43
	v_cvt_pk_bf16_f32 v34, v36, v45
	v_mul_f32_e32 v20, v16, v28
	v_mul_f32_e32 v16, v21, v17
	v_fma_f32 v17, v29, v38, v38
	v_mul_f32_e32 v21, v22, v39
	v_rcp_f32_e32 v17, v17
	v_exp_f32_e32 v21, v21
	v_mul_f32_e32 v28, v23, v39
	v_exp_f32_e32 v28, v28
	v_mul_f32_e32 v29, v16, v17
	v_fma_f32 v16, v21, v38, v38
	v_rcp_f32_e32 v16, v16
	v_cvt_pk_bf16_f32 v35, v37, v35
	v_lshl_add_u64 v[36:37], s[68:69], 0, v[132:133]
	global_store_dwordx4 v[36:37], v[32:35], off sc1
	v_fmamk_f32 v22, v104, 0x3a800000, v148
	v_mul_f32_e32 v21, v18, v16
	v_fma_f32 v32, v40, v38, v38
	v_fma_f32 v33, v41, v38, v38
	v_rcp_f32_e32 v32, v32
	v_rcp_f32_e32 v33, v33
	v_fmac_f32_e32 v38, v28, v38
	v_mul_f32_e32 v16, v23, v19
	v_rsq_f32_e32 v23, v22
	v_rcp_f32_e32 v17, v38
	v_mul_f32_e32 v24, v24, v32
	v_mul_f32_e32 v25, v25, v33
	v_mul_f32_e32 v23, 0xbfb8aa3b, v23
	v_mul_f32_e32 v19, v16, v17
	v_cvt_pk_bf16_f32 v16, v24, v25
	v_mul_f32_e32 v24, v12, v23
	v_mul_f32_e32 v25, v13, v23
	v_mul_f32_e32 v12, v14, v23
	v_mul_f32_e32 v13, v15, v23
	v_exp_f32_e32 v12, v12
	v_exp_f32_e32 v13, v13
	v_mul_f32_e32 v14, v4, v23
	v_exp_f32_e32 v14, v14
	v_fma_f32 v12, v12, v22, v22
	v_fma_f32 v13, v13, v22, v22
	v_rcp_f32_e32 v12, v12
	v_rcp_f32_e32 v13, v13
	v_exp_f32_e32 v24, v24
	v_exp_f32_e32 v25, v25
	v_mul_f32_e32 v10, v10, v12
	v_mul_f32_e32 v11, v11, v13
	v_fma_f32 v12, v14, v22, v22
	v_mul_f32_e32 v13, v5, v23
	v_rcp_f32_e32 v12, v12
	v_exp_f32_e32 v13, v13
	v_cvt_pk_bf16_f32 v17, v26, v27
	v_cvt_pk_bf16_f32 v18, v20, v29
	v_mul_f32_e32 v4, v0, v12
	v_mul_f32_e32 v0, v5, v1
	v_fma_f32 v1, v13, v22, v22
	v_mul_f32_e32 v5, v6, v23
	v_rcp_f32_e32 v1, v1
	v_exp_f32_e32 v5, v5
	v_mul_f32_e32 v12, v7, v23
	v_exp_f32_e32 v12, v12
	v_cvt_pk_bf16_f32 v19, v21, v19
	v_lshl_add_u64 v[20:21], s[68:69], 0, v[134:135]
	v_mul_f32_e32 v13, v0, v1
	v_fma_f32 v0, v5, v22, v22
	global_store_dwordx4 v[20:21], v[16:19], off sc1
	v_rcp_f32_e32 v0, v0
	s_andn2_b64 vcc, exec, s[2:3]
	v_fma_f32 v16, v24, v22, v22
	v_fma_f32 v17, v25, v22, v22
	v_fmac_f32_e32 v22, v12, v22
	v_rcp_f32_e32 v1, v22
	v_rcp_f32_e32 v16, v16
	v_rcp_f32_e32 v17, v17
	v_mul_f32_e32 v5, v2, v0
	v_mul_f32_e32 v0, v7, v3
	v_mul_f32_e32 v3, v0, v1
	v_mul_f32_e32 v8, v8, v16
	v_mul_f32_e32 v9, v9, v17
	v_cvt_pk_bf16_f32 v0, v8, v9
	v_cvt_pk_bf16_f32 v1, v10, v11
	v_cvt_pk_bf16_f32 v2, v4, v13
	v_cvt_pk_bf16_f32 v3, v5, v3
	v_lshl_add_u64 v[4:5], s[68:69], 0, v[136:137]
	s_mov_b64 s[2:3], -1
	global_store_dwordx4 v[4:5], v[0:3], off sc1
	s_cbranch_vccnz .LBB0_137
	s_andn2_b64 vcc, exec, s[52:53]
	s_cbranch_vccnz .LBB0_136
	s_barrier
	s_branch .LBB0_136

; __device__ __forceinline__ unsigned cvt_pk_bf16(float lo, float hi) { unsigned r; asm volatile("v_cvt_pk_bf16_f32 %0, %1, %2" : "=v"(r) : "v"(lo), "v"(hi)); return r; }
;     __device__ __forceinline__ char* hb_at(const Unit& u, int ai, int m, int bj, int wr, int wc, int fr, int fq) const {
;         return (char*)hb + ((size_t)((u.pm * 16 + u.pn * 4 + bj * 2 + (wc >> 1)) * 2 + ai) * HTB) + lds_byte(wr * 64 + m * 16 + fr, (wc & 1) * 32 + 8 * fq); }
;     __device__ __forceinline__ void operator()(f32x4 (&acc)[2][2][4][2], const Unit& u, int wr, int wc, int fr, int fq) const {
;         const int row0 = u.pm * BM + wr * 64 + fr, col0 = u.pn * BM + wc * 32 + 8 * fq;
;         u32x4 pre[2][4][2];
; #pragma unroll
;         for (int ai = 0; ai < 2; ++ai)
; #pragma unroll
;             for (int m = 0; m < 4; ++m)
; #pragma unroll
;                 for (int bj = 0; bj < 2; ++bj) pre[ai][m][bj] = *(const u32x4*)hb_at(u, ai, m, bj, wr, wc, fr, fq);
; #pragma unroll
;         for (int ai = 0; ai < 2; ++ai)
; #pragma unroll
;             for (int m = 0; m < 4; ++m) { const int row = row0 + ai * HALF + m * 16; float s = 0.f;
; #pragma unroll
;                 for (int bj = 0; bj < 2; ++bj) { const size_t o2 = (size_t)row * 1024 + col0 + bj * HALF; const u32x4 p = pre[ai][m][bj]; const f32x4 a0 = acc[ai][bj][m][0], a1 = acc[ai][bj][m][1];
;                     f32x4 o0, o1; o0[0] = bf_lo(p.x) + a0[0] * alpha; o0[1] = bf_hi(p.x) + a0[1] * alpha; o0[2] = bf_lo(p.y) + a0[2] * alpha; o0[3] = bf_hi(p.y) + a0[3] * alpha;
;                     o1[0] = bf_lo(p.z) + a1[0] * alpha; o1[1] = bf_hi(p.z) + a1[1] * alpha; o1[2] = bf_lo(p.w) + a1[2] * alpha; o1[3] = bf_hi(p.w) + a1[3] * alpha;
;                     s += ((o0[0] * o0[0] + o0[1] * o0[1]) + (o0[2] * o0[2] + o0[3] * o0[3])) + ((o1[0] * o1[0] + o1[1] * o1[1]) + (o1[2] * o1[2] + o1[3] * o1[3]));
;                     u32x4 w; w.x = cvt_pk_bf16(o0[0], o0[1]); w.y = cvt_pk_bf16(o0[2], o0[3]); w.z = cvt_pk_bf16(o1[0], o1[1]); w.w = cvt_pk_bf16(o1[2], o1[3]);
;                     *(u32x4*)hb_at(u, ai, m, bj, wr, wc, fr, fq) = w;
;                     if (out) { *(f32x4*)(out + o2) = o0; *(f32x4*)(out + o2 + 4) = o1; } }
;                 s += __shfl_xor(s, 16); s += __shfl_xor(s, 32);
;                 if (ssq && fq == 0) atomicAdd(ssq + row, s); }
.LBB0_229:
	s_lshl_b32 s8, s72, 3
	s_lshl_b32 s9, s76, 5
	s_add_i32 s9, s9, s8
	s_or_b32 s8, s9, s81
	s_ashr_i32 s9, s8, 31
	s_or_b32 s68, s8, 4
	s_lshl_b64 s[72:73], s[8:9], 14
	s_ashr_i32 s69, s68, 31
	v_lshl_add_u64 v[112:113], v[198:199], 0, s[72:73]
	s_lshl_b64 s[74:75], s[68:69], 14
	global_load_dwordx4 v[220:223], v[112:113], off
	v_lshl_add_u64 v[112:113], v[198:199], 0, s[74:75]
	global_load_dwordx4 v[224:227], v[112:113], off
	s_or_b32 s68, s8, 1
	s_or_b32 s8, s8, 5
	s_ashr_i32 s69, s68, 31
	s_ashr_i32 s9, s8, 31
	s_lshl_b64 s[70:71], s[68:69], 14
	s_lshl_b64 s[68:69], s[8:9], 14
	v_lshl_add_u64 v[112:113], v[200:201], 0, s[72:73]
	v_lshl_add_u64 v[114:115], v[202:203], 0, s[72:73]
	v_lshl_add_u64 v[124:125], v[196:197], 0, s[72:73]
	v_lshl_add_u64 v[126:127], v[200:201], 0, s[74:75]
	v_lshl_add_u64 v[136:137], v[202:203], 0, s[74:75]
	v_lshl_add_u64 v[138:139], v[196:197], 0, s[74:75]
	v_lshl_add_u64 v[140:141], v[198:199], 0, s[70:71]
	v_lshl_add_u64 v[142:143], v[198:199], 0, s[68:69]
	v_lshl_add_u64 v[144:145], v[200:201], 0, s[70:71]
	v_lshl_add_u64 v[146:147], v[200:201], 0, s[68:69]
	v_lshl_add_u64 v[216:217], v[202:203], 0, s[70:71]
	v_lshl_add_u64 v[228:229], v[202:203], 0, s[68:69]
	v_lshl_add_u64 v[230:231], v[196:197], 0, s[70:71]
	v_lshl_add_u64 v[232:233], v[196:197], 0, s[68:69]
	global_load_dwordx4 v[180:183], v[112:113], off
	global_load_dwordx4 v[176:179], v[126:127], off
	global_load_dwordx4 v[172:175], v[114:115], off
	global_load_dwordx4 v[168:171], v[136:137], off
	global_load_dwordx4 v[164:167], v[124:125], off
	global_load_dwordx4 v[160:163], v[138:139], off
	global_load_dwordx4 v[156:159], v[140:141], off
	global_load_dwordx4 v[152:155], v[142:143], off
	global_load_dwordx4 v[148:151], v[144:145], off
	s_nop 0
	global_load_dwordx4 v[144:147], v[146:147], off
	s_nop 0
	global_load_dwordx4 v[140:143], v[216:217], off
	global_load_dwordx4 v[136:139], v[228:229], off
	global_load_dwordx4 v[124:127], v[230:231], off
	global_load_dwordx4 v[112:115], v[232:233], off
	s_add_u32 s72, s12, s72
	s_addc_u32 s73, s13, s73
	v_lshl_add_u64 v[216:217], s[72:73], 0, v[190:191]
	s_add_u32 s74, s12, s74
	v_lshl_add_u32 v208, s76, 8, v189
	s_addc_u32 s75, s13, s75
	v_readlane_b32 s99, v246, 6
	s_nop 1
	s_cmp_lt_u32 s99, 4
	s_cbranch_scc0 .Lnoal_1
	s_barrier
.Lnoal_1:
	s_waitcnt vmcnt(0)
	v_lshlrev_b32_e32 v209, 16, v220
	v_and_b32_e32 v219, 0xffff0000, v220
	v_lshlrev_b32_e32 v220, 16, v221
	v_fmac_f32_e32 v220, 0.5, v134
	v_lshlrev_b32_e32 v134, 16, v225
	v_and_b32_e32 v221, 0xffff0000, v221
	v_lshlrev_b32_e32 v228, 16, v222
	v_and_b32_e32 v222, 0xffff0000, v222
	v_lshlrev_b32_e32 v229, 16, v223
	v_and_b32_e32 v223, 0xffff0000, v223
	v_fmac_f32_e32 v134, 0.5, v122
	v_and_b32_e32 v122, 0xffff0000, v226
	v_fmac_f32_e32 v219, 0.5, v133
	v_fmac_f32_e32 v221, 0.5, v135
	v_fmac_f32_e32 v222, 0.5, v129
	v_fmac_f32_e32 v223, 0.5, v131
	v_and_b32_e32 v133, 0xffff0000, v224
	v_and_b32_e32 v135, 0xffff0000, v225
	v_fmac_f32_e32 v122, 0.5, v117
	v_lshlrev_b32_e32 v117, 16, v227
	v_fmac_f32_e32 v209, 0.5, v132
	v_fmac_f32_e32 v228, 0.5, v128
	v_fmac_f32_e32 v229, 0.5, v130
	v_lshlrev_b32_e32 v132, 16, v224
	v_lshlrev_b32_e32 v224, 16, v226
	v_mul_f32_e32 v225, v219, v219
	v_mul_f32_e32 v230, v221, v221
	v_mul_f32_e32 v231, v222, v222
	v_mul_f32_e32 v232, v223, v223
	v_fmac_f32_e32 v133, 0.5, v121
	v_fmac_f32_e32 v135, 0.5, v123
	v_fmac_f32_e32 v117, 0.5, v118
	v_and_b32_e32 v118, 0xffff0000, v227
	v_fmac_f32_e32 v132, 0.5, v120
	v_fmac_f32_e32 v225, v209, v209
	v_fmac_f32_e32 v230, v220, v220
	v_fmac_f32_e32 v231, v228, v228
	v_fmac_f32_e32 v232, v229, v229
	v_fmac_f32_e32 v224, 0.5, v116
	v_fmac_f32_e32 v118, 0.5, v119
	v_mul_f32_e32 v116, v133, v133
	v_mul_f32_e32 v119, v135, v135
	v_add_f32_e32 v120, v225, v230
	v_add_f32_e32 v121, v231, v232
	v_fmac_f32_e32 v116, v132, v132
	v_fmac_f32_e32 v119, v134, v134
	v_add_f32_e32 v120, v120, v121
	v_add_f32_e32 v116, v116, v119
	v_mul_f32_e32 v119, v122, v122
	v_mul_f32_e32 v121, v118, v118
	v_fmac_f32_e32 v119, v224, v224
	v_fmac_f32_e32 v121, v117, v117
	v_add_f32_e32 v119, v119, v121
	v_cvt_pk_bf16_f32 v128, v209, v219
	v_add_f32_e32 v116, v116, v119
	v_and_b32_e32 v121, 64, v215
	v_cvt_pk_bf16_f32 v129, v220, v221
	v_cvt_pk_bf16_f32 v130, v228, v222
	v_cvt_pk_bf16_f32 v131, v229, v223
	global_store_dwordx4 v[216:217], v[128:131], off sc1
	v_add_f32_e32 v119, v120, v116
	v_xor_b32_e32 v116, 16, v215
	v_add_u32_e32 v128, 64, v121
	v_cmp_lt_i32_e32 vcc, v116, v128
	v_cvt_pk_bf16_f32 v120, v132, v133
	v_cvt_pk_bf16_f32 v121, v134, v135
	v_cvt_pk_bf16_f32 v122, v224, v122
	v_cvt_pk_bf16_f32 v123, v117, v118
	v_xor_b32_e32 v117, 32, v215
	s_nop 0
	v_cndmask_b32_e32 v116, v215, v116, vcc
	v_lshlrev_b32_e32 v116, 2, v116
	ds_bpermute_b32 v129, v116, v119
	v_cmp_lt_i32_e32 vcc, v117, v128
	v_ashrrev_i32_e32 v209, 31, v208
	s_waitcnt lgkmcnt(0)
	v_add_f32_e32 v118, v119, v129
	v_cndmask_b32_e32 v117, v215, v117, vcc
	v_lshlrev_b32_e32 v117, 2, v117
	ds_bpermute_b32 v119, v117, v118
	v_lshl_add_u64 v[128:129], s[74:75], 0, v[190:191]
	global_store_dwordx4 v[128:129], v[120:123], off sc1
	s_and_saveexec_b64 s[76:77], s[2:3]
	s_cbranch_execz .LBB0_231
	v_lshl_add_u64 v[120:121], v[208:209], 2, s[10:11]
	s_waitcnt lgkmcnt(0)
	v_add_f32_e32 v118, v118, v119
	global_atomic_add_f32 v[120:121], v118, off

; __device__ __forceinline__ float rstd_of(float ssq) { return __builtin_amdgcn_rsqf(ssq * (1.0f / 1024.0f) + 1e-6f); }
; #define PG8_BAR __builtin_amdgcn_s_barrier()
;     __device__ __forceinline__ void operator()(f32x4 (&acc)[2][2][4][2], const Unit& u, int wr, int wc, int fr, int fq) const {
;         const int row0 = u.pm * BM + wr * 64 + fr, col0 = u.pn * BM + wc * 32 + 8 * fq;
;         const bool sig = u.pn >= 7; const float sc = u.pn < 4 ? qscale : 1.f;
;         float sq[2][4];
; #pragma unroll
;         for (int ai = 0; ai < 2; ++ai)
; #pragma unroll
;             for (int m = 0; m < 4; ++m) sq[ai][m] = ssq[row0 + ai * HALF + m * 16];
; #pragma unroll
;         for (int ai = 0; ai < 2; ++ai)
; #pragma unroll
;             for (int m = 0; m < 4; ++m) { const int row = row0 + ai * HALF + m * 16; const float rs = rstd_of(sq[ai][m]) * sc;
;                 u32x4 g8 = {0u, 0u, 0u, 0u};
; #pragma unroll
;                 for (int bj = 0; bj < 2; ++bj) { f32x4 v0 = acc[ai][bj][m][0] * rs, v1 = acc[ai][bj][m][1] * rs;
; template <class Epi, class Sched, bool ALIGN_EPI = false, bool SP2 = false>
; __device__ __forceinline__ void gemm_phase(PG8_LAS unsigned char* lds, const Gemm g, const Sched& S, const Epi& E) {
;     ...
;         if constexpr (ALIGN_EPI) { if (wr == 0) PG8_BAR; }
.LBB0_318:
	v_lshl_add_u32 v140, s72, 8, v157
	v_ashrrev_i32_e32 v141, 31, v140
	v_lshl_add_u64 v[2:3], v[140:141], 2, s[10:11]
	v_or_b32_e32 v148, 16, v140
	global_load_dword v1, v[2:3], off
	v_ashrrev_i32_e32 v149, 31, v148
	v_or_b32_e32 v146, 32, v140
	v_or_b32_e32 v144, 48, v140
	v_lshl_add_u64 v[142:143], v[148:149], 2, s[10:11]
	v_ashrrev_i32_e32 v147, 31, v146
	v_ashrrev_i32_e32 v145, 31, v144
	v_lshl_add_u64 v[150:151], v[146:147], 2, s[10:11]
	v_lshl_add_u64 v[152:153], v[144:145], 2, s[10:11]
	global_load_dword v169, v[142:143], off
	global_load_dword v168, v[150:151], off
	global_load_dword v167, v[152:153], off
	global_load_dword v166, v[2:3], off offset:512
	global_load_dword v149, v[2:3], off offset:576
	global_load_dword v147, v[2:3], off offset:640
	global_load_dword v141, v[2:3], off offset:704
	s_cmp_gt_i32 s6, 6
	s_cselect_b64 s[74:75], -1, 0
	s_cmp_lt_i32 s6, 7
	s_cselect_b64 s[76:77], -1, 0
	s_cmp_lt_i32 s6, 4
	s_cselect_b64 vcc, -1, 0
	v_lshl_or_b32 v142, s6, 8, v158
	v_mad_i64_i32 v[2:3], s[8:9], v140, s81, 0
	v_cndmask_b32_e32 v145, 1.0, v165, vcc
	v_ashrrev_i32_e32 v143, 31, v142
	v_lshl_add_u64 v[2:3], s[28:29], 0, v[2:3]
	s_mov_b64 s[4:5], -1
	s_and_b64 vcc, exec, s[76:77]
	v_lshl_add_u64 v[150:151], v[142:143], 1, v[2:3]
	v_readlane_b32 s99, v246, 6
	s_nop 1
	s_cmp_lt_u32 s99, 4
	s_cbranch_scc0 .Lnoal_2
	s_barrier
.Lnoal_2:
	s_waitcnt vmcnt(0)
	v_fmamk_f32 v1, v1, 0x3a800000, v164
	v_rsq_f32_e32 v1, v1
	s_nop 0
	v_mul_f32_e32 v152, v145, v1
	v_pk_mul_f32 v[130:131], v[130:131], v[152:153] op_sel_hi:[1,0]
	v_pk_mul_f32 v[128:129], v[128:129], v[152:153] op_sel_hi:[1,0]
	v_pk_mul_f32 v[2:3], v[126:127], v[152:153] op_sel_hi:[1,0]
	v_pk_mul_f32 v[124:125], v[124:125], v[152:153] op_sel_hi:[1,0]
	s_cbranch_vccz .LBB0_320
	v_cvt_pk_bf16_f32 v170, v128, v129
	v_cvt_pk_bf16_f32 v171, v130, v131
	v_cvt_pk_bf16_f32 v172, v124, v125
	v_cvt_pk_bf16_f32 v173, v2, v3
	global_store_dwordx4 v[150:151], v[170:173], off sc1
	s_mov_b64 s[4:5], 0

; __device__ __forceinline__ float bf_lo(unsigned w) { return __uint_as_float(w << 16); }
;     __device__ __forceinline__ char* mg_at(const Unit& u, int ai, int m, int bj, int wr, int wc, int fr, int fq) const {
;         return (char*)MG + ((size_t)((u.pm * 16 + u.pn * 4 + bj * 2 + (wc >> 1)) * 2 + ai) * HTB) + lds_byte(wr * 64 + m * 16 + fr, (wc & 1) * 32 + 8 * fq); }
;     __device__ __forceinline__ void operator()(f32x4 (&acc)[2][2][4][2], const Unit& u, int wr, int wc, int fr, int fq) const {
;         const int row0 = u.pm * BM + wr * 64 + fr, col0 = u.pn * BM + wc * 32 + 8 * fq;
;         const float q = 1.0f / 255.0f;
;         u32x4 gw[2][4];
; #pragma unroll
;         for (int ai = 0; ai < 2; ++ai)
; #pragma unroll
;             for (int m = 0; m < 4; ++m) gw[ai][m] = *(const u32x4*)(G8 + ((size_t)(((u.pm * 8 + gsel + u.pn) * 8 + (wr * 4 + wc)) * 8 + (ai * 4 + m)) * 1024) + (fq * 16 + fr) * 16);
;         if (ACCUM) {
;             int chain = row0; float dep = acc[0][0][0][0][0];
; #pragma unroll
;             for (int ai = 0; ai < 2; ++ai) { u32x4 ow[4][2];
;                 asm volatile("" : "+v"(chain) : "v"(dep));
; #pragma unroll
;                 for (int m = 0; m < 4; ++m)
; #pragma unroll
;                     for (int bj = 0; bj < 2; ++bj) ow[m][bj] = *(const u32x4*)(mg_at(u, ai, m, bj, wr, wc, fr, fq) + (chain - row0));
; #pragma unroll
;                 for (int m = 0; m < 4; ++m)
; #pragma unroll
;                     for (int bj = 0; bj < 2; ++bj) { const u32x4 gq = gw[ai][m]; u32x2 g; g.x = bj ? gq.z : gq.x; g.y = bj ? gq.w : gq.y; const u32x4 o = ow[m][bj]; f32x4& a0 = acc[ai][bj][m][0]; f32x4& a1 = acc[ai][bj][m][1];
;                         a0[0] = a0[0] * (ub(g.x, 0) * q) + bf_lo(o.x); a0[1] = a0[1] * (ub(g.x, 1) * q) + bf_hi(o.x); a0[2] = a0[2] * (ub(g.x, 2) * q) + bf_lo(o.y); a0[3] = a0[3] * (ub(g.x, 3) * q) + bf_hi(o.y);
;                         a1[0] = a1[0] * (ub(g.y, 0) * q) + bf_lo(o.z); a1[1] = a1[1] * (ub(g.y, 1) * q) + bf_hi(o.z); a1[2] = a1[2] * (ub(g.y, 2) * q) + bf_lo(o.w); a1[3] = a1[3] * (ub(g.y, 3) * q) + bf_hi(o.w);
;                         asm volatile("" : "+v"(a0), "+v"(a1)); }
;                 dep = acc[ai][1][3][1][3]; }
;         } else {
; #pragma unroll
;             for (int ai = 0; ai < 2; ++ai)
; #pragma unroll
;                 for (int m = 0; m < 4; ++m)
; #pragma unroll
.LBB0_649:
	s_lshl_b32 s1, s89, 6
	s_lshl_b32 s0, s88, 9
	s_add_i32 s1, s76, s1
	s_add_i32 s0, s1, s0
	s_ashr_i32 s1, s0, 31
	s_lshl_b64 s[8:9], s[0:1], 10
	v_lshl_add_u64 v[128:129], v[172:173], 0, s[8:9]
	global_load_dwordx4 v[156:159], v[128:129], off
	s_or_b32 s8, s0, 1
	s_ashr_i32 s9, s8, 31
	s_lshl_b64 s[8:9], s[8:9], 10
	v_lshl_add_u64 v[128:129], v[172:173], 0, s[8:9]
	global_load_dwordx4 v[152:155], v[128:129], off
	s_or_b32 s8, s0, 2
	s_ashr_i32 s9, s8, 31
	s_lshl_b64 s[8:9], s[8:9], 10
	v_lshl_add_u64 v[128:129], v[172:173], 0, s[8:9]
	global_load_dwordx4 v[148:151], v[128:129], off
	s_or_b32 s8, s0, 3
	s_ashr_i32 s9, s8, 31
	s_lshl_b64 s[8:9], s[8:9], 10
	v_lshl_add_u64 v[128:129], v[172:173], 0, s[8:9]
	global_load_dwordx4 v[144:147], v[128:129], off
	s_or_b32 s8, s0, 4
	s_ashr_i32 s9, s8, 31
	s_lshl_b64 s[8:9], s[8:9], 10
	v_lshl_add_u64 v[128:129], v[172:173], 0, s[8:9]
	global_load_dwordx4 v[140:143], v[128:129], off
	s_or_b32 s8, s0, 5
	s_ashr_i32 s9, s8, 31
	s_lshl_b64 s[8:9], s[8:9], 10
	v_lshl_add_u64 v[128:129], v[172:173], 0, s[8:9]
	global_load_dwordx4 v[136:139], v[128:129], off
	s_or_b32 s8, s0, 6
	s_or_b32 s0, s0, 7
	s_ashr_i32 s1, s0, 31
	s_ashr_i32 s9, s8, 31
	s_lshl_b64 s[0:1], s[0:1], 10
	s_lshl_b64 s[8:9], s[8:9], 10
	v_lshl_add_u64 v[132:133], v[172:173], 0, s[0:1]
	global_load_dwordx4 v[132:135], v[132:133], off
	v_lshl_add_u64 v[128:129], v[172:173], 0, s[8:9]
	global_load_dwordx4 v[128:131], v[128:129], off
	s_lshl_b32 s0, s89, 3
	s_lshl_b32 s1, s88, 5
	s_add_i32 s1, s1, s0
	s_or_b32 s0, s1, s73
	s_ashr_i32 s1, s0, 31
	s_lshl_b64 s[8:9], s[0:1], 14
	s_add_u32 s66, s6, s8
	s_addc_u32 s67, s7, s9
	s_or_b32 s8, s0, 4
	s_ashr_i32 s9, s8, 31
	s_lshl_b64 s[8:9], s[8:9], 14
	s_add_u32 s68, s6, s8
	s_addc_u32 s69, s7, s9
	s_or_b32 s8, s0, 1
	s_ashr_i32 s9, s8, 31
	s_lshl_b64 s[8:9], s[8:9], 14
	v_readlane_b32 s99, v246, 6
	s_nop 1
	s_cmp_lt_u32 s99, 4
	s_cbranch_scc0 .Lnoal_3
	s_barrier
.Lnoal_3:
	s_waitcnt vmcnt(0)
	v_cvt_f32_ubyte3_e32 v203, v156
	v_cvt_f32_ubyte2_e32 v202, v156
	v_cvt_f32_ubyte1_e32 v205, v156
	v_cvt_f32_ubyte0_e32 v204, v156
	v_pk_mul_f32 v[204:205], v[204:205], s[58:59] op_sel_hi:[1,0]
	v_pk_mul_f32 v[202:203], v[202:203], s[58:59] op_sel_hi:[1,0]
	v_pk_mul_f32 v[124:125], v[124:125], v[204:205]
	v_pk_mul_f32 v[126:127], v[126:127], v[202:203]
	v_cvt_f32_ubyte3_e32 v203, v157
	v_cvt_f32_ubyte2_e32 v202, v157
	v_cvt_f32_ubyte1_e32 v205, v157
	v_cvt_f32_ubyte0_e32 v204, v157
	v_pk_mul_f32 v[156:157], v[204:205], s[58:59] op_sel_hi:[1,0]
	v_pk_mul_f32 v[202:203], v[202:203], s[58:59] op_sel_hi:[1,0]
	v_pk_mul_f32 v[120:121], v[120:121], v[156:157]
	v_pk_mul_f32 v[122:123], v[122:123], v[202:203]
	v_cvt_f32_ubyte3_e32 v157, v158
	v_cvt_f32_ubyte2_e32 v156, v158
	v_cvt_f32_ubyte1_e32 v203, v158
	v_cvt_f32_ubyte0_e32 v202, v158
	v_pk_mul_f32 v[202:203], v[202:203], s[58:59] op_sel_hi:[1,0]
	v_pk_mul_f32 v[156:157], v[156:157], s[58:59] op_sel_hi:[1,0]
	v_pk_mul_f32 v[116:117], v[116:117], v[202:203]
	v_pk_mul_f32 v[118:119], v[118:119], v[156:157]
	v_cvt_f32_ubyte3_e32 v157, v159
	v_cvt_f32_ubyte2_e32 v156, v159
	v_cvt_f32_ubyte1_e32 v203, v159
	v_cvt_f32_ubyte0_e32 v202, v159
	v_pk_mul_f32 v[158:159], v[202:203], s[58:59] op_sel_hi:[1,0]
	v_pk_mul_f32 v[156:157], v[156:157], s[58:59] op_sel_hi:[1,0]
	v_pk_mul_f32 v[112:113], v[112:113], v[158:159]
	v_pk_mul_f32 v[114:115], v[114:115], v[156:157]
	v_cvt_f32_ubyte3_e32 v157, v152
	v_cvt_f32_ubyte2_e32 v156, v152
	v_cvt_f32_ubyte1_e32 v159, v152
	v_cvt_f32_ubyte0_e32 v158, v152
	v_pk_mul_f32 v[158:159], v[158:159], s[58:59] op_sel_hi:[1,0]
	v_pk_mul_f32 v[156:157], v[156:157], s[58:59] op_sel_hi:[1,0]
	v_pk_mul_f32 v[108:109], v[108:109], v[158:159]
	v_pk_mul_f32 v[110:111], v[110:111], v[156:157]
	v_cvt_f32_ubyte3_e32 v157, v153
	v_cvt_f32_ubyte2_e32 v156, v153
	v_cvt_f32_ubyte1_e32 v159, v153
	v_cvt_f32_ubyte0_e32 v158, v153
	v_pk_mul_f32 v[152:153], v[158:159], s[58:59] op_sel_hi:[1,0]
	v_pk_mul_f32 v[156:157], v[156:157], s[58:59] op_sel_hi:[1,0]
	v_pk_mul_f32 v[104:105], v[104:105], v[152:153]
	v_pk_mul_f32 v[106:107], v[106:107], v[156:157]
	v_cvt_f32_ubyte3_e32 v153, v154
	v_cvt_f32_ubyte2_e32 v152, v154
	v_cvt_f32_ubyte1_e32 v157, v154
	v_cvt_f32_ubyte0_e32 v156, v154
	v_pk_mul_f32 v[156:157], v[156:157], s[58:59] op_sel_hi:[1,0]
	v_pk_mul_f32 v[152:153], v[152:153], s[58:59] op_sel_hi:[1,0]
	v_pk_mul_f32 v[100:101], v[100:101], v[156:157]
	v_pk_mul_f32 v[102:103], v[102:103], v[152:153]
	v_cvt_f32_ubyte3_e32 v153, v155
	v_cvt_f32_ubyte2_e32 v152, v155
	v_cvt_f32_ubyte1_e32 v157, v155
	v_cvt_f32_ubyte0_e32 v156, v155
	v_pk_mul_f32 v[154:155], v[156:157], s[58:59] op_sel_hi:[1,0]
	v_pk_mul_f32 v[152:153], v[152:153], s[58:59] op_sel_hi:[1,0]
	v_pk_mul_f32 v[92:93], v[92:93], v[154:155]
	v_pk_mul_f32 v[94:95], v[94:95], v[152:153]
	v_cvt_f32_ubyte3_e32 v153, v148
	v_cvt_f32_ubyte2_e32 v152, v148
	v_cvt_f32_ubyte1_e32 v155, v148
	v_cvt_f32_ubyte0_e32 v154, v148
	v_pk_mul_f32 v[154:155], v[154:155], s[58:59] op_sel_hi:[1,0]
	v_pk_mul_f32 v[152:153], v[152:153], s[58:59] op_sel_hi:[1,0]
	v_pk_mul_f32 v[96:97], v[96:97], v[154:155]
	v_pk_mul_f32 v[98:99], v[98:99], v[152:153]
	v_cvt_f32_ubyte3_e32 v153, v149
	v_cvt_f32_ubyte2_e32 v152, v149
	v_cvt_f32_ubyte1_e32 v155, v149
	v_cvt_f32_ubyte0_e32 v154, v149
	v_pk_mul_f32 v[148:149], v[154:155], s[58:59] op_sel_hi:[1,0]
	v_pk_mul_f32 v[152:153], v[152:153], s[58:59] op_sel_hi:[1,0]
	v_pk_mul_f32 v[88:89], v[88:89], v[148:149]
	v_pk_mul_f32 v[90:91], v[90:91], v[152:153]
	v_cvt_f32_ubyte3_e32 v149, v150
	v_cvt_f32_ubyte2_e32 v148, v150
	v_cvt_f32_ubyte1_e32 v153, v150
	v_cvt_f32_ubyte0_e32 v152, v150
;     __device__ static __forceinline__ float ub(unsigned w, int k) { return (float)((w >> (8 * k)) & 0xffu); }
;     __device__ __forceinline__ void operator()(f32x4 (&acc)[2][2][4][2], const Unit& u, int wr, int wc, int fr, int fq) const {
;     ...
;                     for (int bj = 0; bj < 2; ++bj) { const u32x4 gq = gw[ai][m]; u32x2 g; g.x = bj ? gq.z : gq.x; g.y = bj ? gq.w : gq.y; f32x4& a0 = acc[ai][bj][m][0]; f32x4& a1 = acc[ai][bj][m][1];
;                         a0[0] *= ub(g.x, 0) * q; a0[1] *= ub(g.x, 1) * q; a0[2] *= ub(g.x, 2) * q; a0[3] *= ub(g.x, 3) * q; a1[0] *= ub(g.y, 0) * q; a1[1] *= ub(g.y, 1) * q; a1[2] *= ub(g.y, 2) * q; a1[3] *= ub(g.y, 3) * q;
;                         asm volatile("" : "+v"(a0), "+v"(a1)); }
	v_pk_mul_f32 v[152:153], v[152:153], s[58:59] op_sel_hi:[1,0]
	v_pk_mul_f32 v[148:149], v[148:149], s[58:59] op_sel_hi:[1,0]
	v_pk_mul_f32 v[84:85], v[84:85], v[152:153]
	v_pk_mul_f32 v[86:87], v[86:87], v[148:149]
	v_cvt_f32_ubyte3_e32 v149, v151
	v_cvt_f32_ubyte2_e32 v148, v151
	v_cvt_f32_ubyte1_e32 v153, v151
	v_cvt_f32_ubyte0_e32 v152, v151
	v_pk_mul_f32 v[150:151], v[152:153], s[58:59] op_sel_hi:[1,0]
	v_pk_mul_f32 v[148:149], v[148:149], s[58:59] op_sel_hi:[1,0]
	v_pk_mul_f32 v[76:77], v[76:77], v[150:151]
	v_pk_mul_f32 v[78:79], v[78:79], v[148:149]
	v_cvt_f32_ubyte3_e32 v149, v144
	v_cvt_f32_ubyte2_e32 v148, v144
	v_cvt_f32_ubyte1_e32 v151, v144
	v_cvt_f32_ubyte0_e32 v150, v144
	v_pk_mul_f32 v[150:151], v[150:151], s[58:59] op_sel_hi:[1,0]
	v_pk_mul_f32 v[148:149], v[148:149], s[58:59] op_sel_hi:[1,0]
	v_pk_mul_f32 v[80:81], v[80:81], v[150:151]
	v_pk_mul_f32 v[82:83], v[82:83], v[148:149]
	v_cvt_f32_ubyte3_e32 v149, v145
	v_cvt_f32_ubyte2_e32 v148, v145
	v_cvt_f32_ubyte1_e32 v151, v145
	v_cvt_f32_ubyte0_e32 v150, v145
	v_pk_mul_f32 v[144:145], v[150:151], s[58:59] op_sel_hi:[1,0]
	v_pk_mul_f32 v[148:149], v[148:149], s[58:59] op_sel_hi:[1,0]
	v_pk_mul_f32 v[72:73], v[72:73], v[144:145]
	v_pk_mul_f32 v[74:75], v[74:75], v[148:149]
	v_cvt_f32_ubyte3_e32 v145, v146
	v_cvt_f32_ubyte2_e32 v144, v146
	v_cvt_f32_ubyte1_e32 v149, v146
	v_cvt_f32_ubyte0_e32 v148, v146
	v_pk_mul_f32 v[148:149], v[148:149], s[58:59] op_sel_hi:[1,0]
	v_pk_mul_f32 v[144:145], v[144:145], s[58:59] op_sel_hi:[1,0]
	v_pk_mul_f32 v[68:69], v[68:69], v[148:149]
	v_pk_mul_f32 v[70:71], v[70:71], v[144:145]
	v_cvt_f32_ubyte3_e32 v145, v147
	v_cvt_f32_ubyte2_e32 v144, v147
	v_cvt_f32_ubyte1_e32 v149, v147
	v_cvt_f32_ubyte0_e32 v148, v147
	v_pk_mul_f32 v[146:147], v[148:149], s[58:59] op_sel_hi:[1,0]
	v_pk_mul_f32 v[144:145], v[144:145], s[58:59] op_sel_hi:[1,0]
	v_pk_mul_f32 v[64:65], v[64:65], v[146:147]
	v_pk_mul_f32 v[66:67], v[66:67], v[144:145]
	v_cvt_f32_ubyte3_e32 v145, v140
	v_cvt_f32_ubyte2_e32 v144, v140
	v_cvt_f32_ubyte1_e32 v147, v140
	v_cvt_f32_ubyte0_e32 v146, v140
	v_pk_mul_f32 v[146:147], v[146:147], s[58:59] op_sel_hi:[1,0]
	v_pk_mul_f32 v[144:145], v[144:145], s[58:59] op_sel_hi:[1,0]
	v_pk_mul_f32 v[60:61], v[60:61], v[146:147]
	v_pk_mul_f32 v[62:63], v[62:63], v[144:145]
	v_cvt_f32_ubyte3_e32 v145, v141
	v_cvt_f32_ubyte2_e32 v144, v141
	v_cvt_f32_ubyte1_e32 v147, v141
	v_cvt_f32_ubyte0_e32 v146, v141
	v_pk_mul_f32 v[140:141], v[146:147], s[58:59] op_sel_hi:[1,0]
	v_pk_mul_f32 v[144:145], v[144:145], s[58:59] op_sel_hi:[1,0]
	v_pk_mul_f32 v[56:57], v[56:57], v[140:141]
	v_pk_mul_f32 v[58:59], v[58:59], v[144:145]
	v_cvt_f32_ubyte3_e32 v141, v142
	v_cvt_f32_ubyte2_e32 v140, v142
	v_cvt_f32_ubyte1_e32 v145, v142
	v_cvt_f32_ubyte0_e32 v144, v142
	v_pk_mul_f32 v[144:145], v[144:145], s[58:59] op_sel_hi:[1,0]
	v_pk_mul_f32 v[140:141], v[140:141], s[58:59] op_sel_hi:[1,0]
	v_pk_mul_f32 v[52:53], v[52:53], v[144:145]
	v_pk_mul_f32 v[54:55], v[54:55], v[140:141]
	v_cvt_f32_ubyte3_e32 v141, v143
	v_cvt_f32_ubyte2_e32 v140, v143
	v_cvt_f32_ubyte1_e32 v145, v143
	v_cvt_f32_ubyte0_e32 v144, v143
	v_pk_mul_f32 v[142:143], v[144:145], s[58:59] op_sel_hi:[1,0]
	v_pk_mul_f32 v[140:141], v[140:141], s[58:59] op_sel_hi:[1,0]
	v_pk_mul_f32 v[44:45], v[44:45], v[142:143]
	v_pk_mul_f32 v[46:47], v[46:47], v[140:141]
	v_cvt_f32_ubyte3_e32 v141, v136
	v_cvt_f32_ubyte2_e32 v140, v136
	v_cvt_f32_ubyte1_e32 v143, v136
	v_cvt_f32_ubyte0_e32 v142, v136
	v_pk_mul_f32 v[142:143], v[142:143], s[58:59] op_sel_hi:[1,0]
	v_pk_mul_f32 v[140:141], v[140:141], s[58:59] op_sel_hi:[1,0]
	v_pk_mul_f32 v[48:49], v[48:49], v[142:143]
	v_pk_mul_f32 v[50:51], v[50:51], v[140:141]
	v_cvt_f32_ubyte3_e32 v141, v137
	v_cvt_f32_ubyte2_e32 v140, v137
	v_cvt_f32_ubyte1_e32 v143, v137
	v_cvt_f32_ubyte0_e32 v142, v137
	v_pk_mul_f32 v[136:137], v[142:143], s[58:59] op_sel_hi:[1,0]
	v_pk_mul_f32 v[140:141], v[140:141], s[58:59] op_sel_hi:[1,0]
	v_pk_mul_f32 v[40:41], v[40:41], v[136:137]
	v_pk_mul_f32 v[42:43], v[42:43], v[140:141]
	v_cvt_f32_ubyte3_e32 v137, v138
	v_cvt_f32_ubyte2_e32 v136, v138
	v_cvt_f32_ubyte1_e32 v141, v138
	v_cvt_f32_ubyte0_e32 v140, v138
	v_pk_mul_f32 v[140:141], v[140:141], s[58:59] op_sel_hi:[1,0]
	v_pk_mul_f32 v[136:137], v[136:137], s[58:59] op_sel_hi:[1,0]
	v_pk_mul_f32 v[36:37], v[36:37], v[140:141]
	v_pk_mul_f32 v[38:39], v[38:39], v[136:137]
	v_cvt_f32_ubyte3_e32 v137, v139
	v_cvt_f32_ubyte2_e32 v136, v139
	v_cvt_f32_ubyte1_e32 v141, v139
	v_cvt_f32_ubyte0_e32 v140, v139
	v_pk_mul_f32 v[138:139], v[140:141], s[58:59] op_sel_hi:[1,0]
	v_pk_mul_f32 v[136:137], v[136:137], s[58:59] op_sel_hi:[1,0]
	v_pk_mul_f32 v[28:29], v[28:29], v[138:139]
	v_pk_mul_f32 v[30:31], v[30:31], v[136:137]
	v_cvt_f32_ubyte3_e32 v137, v128
	v_cvt_f32_ubyte2_e32 v136, v128
	v_cvt_f32_ubyte1_e32 v139, v128
	v_cvt_f32_ubyte0_e32 v138, v128
	v_pk_mul_f32 v[138:139], v[138:139], s[58:59] op_sel_hi:[1,0]
	v_pk_mul_f32 v[136:137], v[136:137], s[58:59] op_sel_hi:[1,0]
	v_pk_mul_f32 v[32:33], v[32:33], v[138:139]
	v_pk_mul_f32 v[34:35], v[34:35], v[136:137]
	v_cvt_f32_ubyte3_e32 v137, v129
	v_cvt_f32_ubyte2_e32 v136, v129
	v_cvt_f32_ubyte1_e32 v139, v129
	v_cvt_f32_ubyte0_e32 v138, v129
	v_pk_mul_f32 v[128:129], v[138:139], s[58:59] op_sel_hi:[1,0]
	v_pk_mul_f32 v[136:137], v[136:137], s[58:59] op_sel_hi:[1,0]
	v_pk_mul_f32 v[24:25], v[24:25], v[128:129]
	v_pk_mul_f32 v[26:27], v[26:27], v[136:137]
	v_cvt_f32_ubyte3_e32 v129, v130
	v_cvt_f32_ubyte2_e32 v128, v130
	v_cvt_f32_ubyte1_e32 v137, v130
	v_cvt_f32_ubyte0_e32 v136, v130
	v_pk_mul_f32 v[136:137], v[136:137], s[58:59] op_sel_hi:[1,0]
; __device__ __forceinline__ unsigned cvt_pk_bf16(float lo, float hi) { unsigned r; asm volatile("v_cvt_pk_bf16_f32 %0, %1, %2" : "=v"(r) : "v"(lo), "v"(hi)); return r; }
;     __device__ static __forceinline__ float ub(unsigned w, int k) { return (float)((w >> (8 * k)) & 0xffu); }
; #define PG8_BAR __builtin_amdgcn_s_barrier()
;     __device__ __forceinline__ void operator()(f32x4 (&acc)[2][2][4][2], const Unit& u, int wr, int wc, int fr, int fq) const {
;     ...
;                     for (int bj = 0; bj < 2; ++bj) { const u32x4 gq = gw[ai][m]; u32x2 g; g.x = bj ? gq.z : gq.x; g.y = bj ? gq.w : gq.y; f32x4& a0 = acc[ai][bj][m][0]; f32x4& a1 = acc[ai][bj][m][1];
;                         a0[0] *= ub(g.x, 0) * q; a0[1] *= ub(g.x, 1) * q; a0[2] *= ub(g.x, 2) * q; a0[3] *= ub(g.x, 3) * q; a1[0] *= ub(g.y, 0) * q; a1[1] *= ub(g.y, 1) * q; a1[2] *= ub(g.y, 2) * q; a1[3] *= ub(g.y, 3) * q;
;                         asm volatile("" : "+v"(a0), "+v"(a1)); }
;         }
; #pragma unroll
;         for (int ai = 0; ai < 2; ++ai)
; #pragma unroll
;             for (int m = 0; m < 4; ++m)
; #pragma unroll
;                 for (int bj = 0; bj < 2; ++bj) { const f32x4 a0 = acc[ai][bj][m][0], a1 = acc[ai][bj][m][1];
;                     u32x4 w; w.x = cvt_pk_bf16(a0[0], a0[1]); w.y = cvt_pk_bf16(a0[2], a0[3]); w.z = cvt_pk_bf16(a1[0], a1[1]); w.w = cvt_pk_bf16(a1[2], a1[3]);
;                     *(u32x4*)mg_at(u, ai, m, bj, wr, wc, fr, fq) = w; }
; template <class Epi, class Sched, bool ALIGN_EPI = false, bool SP2 = false>
; __device__ __forceinline__ void gemm_phase(PG8_LAS unsigned char* lds, const Gemm g, const Sched& S, const Epi& E) {
;     ...
;         if (!has_next) break;
; #pragma unroll
;         for (int a = 0; a < 2; ++a)
; #pragma unroll
;             for (int b = 0; b < 2; ++b)
; #pragma unroll
;                 for (int m = 0; m < 4; ++m)
; #pragma unroll
;                     for (int n = 0; n < 2; ++n) acc[a][b][m][n] = (f32x4){0.f, 0.f, 0.f, 0.f};
;         cur = nxt; cA = nA; cB = nB; ++ui;
;         if constexpr (ALIGN_EPI) { if (wr == 1) PG8_BAR; }
	v_pk_mul_f32 v[128:129], v[128:129], s[58:59] op_sel_hi:[1,0]
	v_pk_mul_f32 v[20:21], v[20:21], v[136:137]
	v_pk_mul_f32 v[22:23], v[22:23], v[128:129]
	v_cvt_f32_ubyte3_e32 v129, v131
	v_cvt_f32_ubyte2_e32 v128, v131
	v_cvt_f32_ubyte1_e32 v137, v131
	v_cvt_f32_ubyte0_e32 v136, v131
	v_pk_mul_f32 v[130:131], v[136:137], s[58:59] op_sel_hi:[1,0]
	v_pk_mul_f32 v[128:129], v[128:129], s[58:59] op_sel_hi:[1,0]
	v_pk_mul_f32 v[12:13], v[12:13], v[130:131]
	v_pk_mul_f32 v[14:15], v[14:15], v[128:129]
	v_cvt_f32_ubyte3_e32 v129, v132
	v_cvt_f32_ubyte2_e32 v128, v132
	v_cvt_f32_ubyte1_e32 v131, v132
	v_cvt_f32_ubyte0_e32 v130, v132
	v_pk_mul_f32 v[130:131], v[130:131], s[58:59] op_sel_hi:[1,0]
	v_pk_mul_f32 v[128:129], v[128:129], s[58:59] op_sel_hi:[1,0]
	v_pk_mul_f32 v[16:17], v[16:17], v[130:131]
	v_pk_mul_f32 v[18:19], v[18:19], v[128:129]
	v_cvt_f32_ubyte3_e32 v129, v133
	v_cvt_f32_ubyte2_e32 v128, v133
	v_cvt_f32_ubyte1_e32 v131, v133
	v_cvt_f32_ubyte0_e32 v130, v133
	v_pk_mul_f32 v[130:131], v[130:131], s[58:59] op_sel_hi:[1,0]
	v_pk_mul_f32 v[128:129], v[128:129], s[58:59] op_sel_hi:[1,0]
	v_pk_mul_f32 v[8:9], v[8:9], v[130:131]
	v_pk_mul_f32 v[10:11], v[10:11], v[128:129]
	v_cvt_f32_ubyte3_e32 v129, v134
	v_cvt_f32_ubyte2_e32 v128, v134
	v_cvt_f32_ubyte1_e32 v131, v134
	v_cvt_f32_ubyte0_e32 v130, v134
	v_pk_mul_f32 v[130:131], v[130:131], s[58:59] op_sel_hi:[1,0]
	v_pk_mul_f32 v[128:129], v[128:129], s[58:59] op_sel_hi:[1,0]
	v_pk_mul_f32 v[4:5], v[4:5], v[130:131]
	v_pk_mul_f32 v[6:7], v[6:7], v[128:129]
	v_cvt_f32_ubyte3_e32 v129, v135
	v_cvt_f32_ubyte2_e32 v128, v135
	v_cvt_f32_ubyte1_e32 v131, v135
	v_cvt_f32_ubyte0_e32 v130, v135
	v_pk_mul_f32 v[130:131], v[130:131], s[58:59] op_sel_hi:[1,0]
	v_pk_mul_f32 v[128:129], v[128:129], s[58:59] op_sel_hi:[1,0]
	v_pk_mul_f32 v[0:1], v[0:1], v[130:131]
	v_pk_mul_f32 v[2:3], v[2:3], v[128:129]
	s_nop 0
	v_cvt_pk_bf16_f32 v124, v124, v125
	v_cvt_pk_bf16_f32 v125, v126, v127
	v_cvt_pk_bf16_f32 v126, v120, v121
	v_lshl_add_u64 v[120:121], s[66:67], 0, v[164:165]
	v_cvt_pk_bf16_f32 v127, v122, v123
	global_store_dwordx4 v[120:121], v[124:127], off sc1
	v_cvt_pk_bf16_f32 v116, v116, v117
	v_cvt_pk_bf16_f32 v117, v118, v119
	v_cvt_pk_bf16_f32 v118, v112, v113
	v_lshl_add_u64 v[112:113], s[68:69], 0, v[164:165]
	v_cvt_pk_bf16_f32 v119, v114, v115
	global_store_dwordx4 v[112:113], v[116:119], off sc1
	v_cvt_pk_bf16_f32 v108, v108, v109
	v_cvt_pk_bf16_f32 v109, v110, v111
	v_cvt_pk_bf16_f32 v110, v104, v105
	v_lshl_add_u64 v[104:105], s[66:67], 0, v[166:167]
	v_cvt_pk_bf16_f32 v111, v106, v107
	global_store_dwordx4 v[104:105], v[108:111], off sc1
	v_cvt_pk_bf16_f32 v100, v100, v101
	v_cvt_pk_bf16_f32 v101, v102, v103
	v_cvt_pk_bf16_f32 v102, v92, v93
	v_lshl_add_u64 v[92:93], s[68:69], 0, v[166:167]
	v_cvt_pk_bf16_f32 v103, v94, v95
	global_store_dwordx4 v[92:93], v[100:103], off sc1
	v_cvt_pk_bf16_f32 v92, v96, v97
	v_cvt_pk_bf16_f32 v93, v98, v99
	v_cvt_pk_bf16_f32 v94, v88, v89
	v_lshl_add_u64 v[88:89], s[66:67], 0, v[168:169]
	v_cvt_pk_bf16_f32 v95, v90, v91
	global_store_dwordx4 v[88:89], v[92:95], off sc1
	v_cvt_pk_bf16_f32 v84, v84, v85
	v_cvt_pk_bf16_f32 v85, v86, v87
	v_cvt_pk_bf16_f32 v86, v76, v77
	v_lshl_add_u64 v[76:77], s[68:69], 0, v[168:169]
	v_cvt_pk_bf16_f32 v87, v78, v79
	global_store_dwordx4 v[76:77], v[84:87], off sc1
	v_cvt_pk_bf16_f32 v76, v80, v81
	v_cvt_pk_bf16_f32 v77, v82, v83
	v_cvt_pk_bf16_f32 v78, v72, v73
	v_lshl_add_u64 v[72:73], s[66:67], 0, v[170:171]
	s_add_u32 s66, s6, s8
	s_addc_u32 s67, s7, s9
	s_or_b32 s0, s0, 5
	s_ashr_i32 s1, s0, 31
	s_lshl_b64 s[0:1], s[0:1], 14
	v_cvt_pk_bf16_f32 v79, v74, v75
	global_store_dwordx4 v[72:73], v[76:79], off sc1
	v_cvt_pk_bf16_f32 v68, v68, v69
	v_cvt_pk_bf16_f32 v69, v70, v71
	v_cvt_pk_bf16_f32 v70, v64, v65
	v_lshl_add_u64 v[64:65], s[68:69], 0, v[170:171]
	s_add_u32 s0, s6, s0
	v_cvt_pk_bf16_f32 v71, v66, v67
	global_store_dwordx4 v[64:65], v[68:71], off sc1
	v_cvt_pk_bf16_f32 v60, v60, v61
	v_cvt_pk_bf16_f32 v61, v62, v63
	v_cvt_pk_bf16_f32 v62, v56, v57
	v_lshl_add_u64 v[56:57], s[66:67], 0, v[164:165]
	s_addc_u32 s1, s7, s1
	v_cvt_pk_bf16_f32 v63, v58, v59
	global_store_dwordx4 v[56:57], v[60:63], off sc1
	v_cvt_pk_bf16_f32 v52, v52, v53
	v_cvt_pk_bf16_f32 v53, v54, v55
	v_cvt_pk_bf16_f32 v54, v44, v45
	v_lshl_add_u64 v[44:45], s[0:1], 0, v[164:165]
	v_cvt_pk_bf16_f32 v55, v46, v47
	global_store_dwordx4 v[44:45], v[52:55], off sc1
	v_cvt_pk_bf16_f32 v44, v48, v49
	v_cvt_pk_bf16_f32 v45, v50, v51
	v_cvt_pk_bf16_f32 v46, v40, v41
	v_lshl_add_u64 v[40:41], s[66:67], 0, v[166:167]
	v_cvt_pk_bf16_f32 v47, v42, v43
	global_store_dwordx4 v[40:41], v[44:47], off sc1
	v_cvt_pk_bf16_f32 v36, v36, v37
	v_cvt_pk_bf16_f32 v37, v38, v39
	v_cvt_pk_bf16_f32 v38, v28, v29
	v_lshl_add_u64 v[28:29], s[0:1], 0, v[166:167]
	v_cvt_pk_bf16_f32 v39, v30, v31
	global_store_dwordx4 v[28:29], v[36:39], off sc1
	v_cvt_pk_bf16_f32 v28, v32, v33
	v_cvt_pk_bf16_f32 v29, v34, v35
	v_cvt_pk_bf16_f32 v30, v24, v25
	v_lshl_add_u64 v[24:25], s[66:67], 0, v[168:169]
	v_cvt_pk_bf16_f32 v31, v26, v27
	global_store_dwordx4 v[24:25], v[28:31], off sc1
	v_cvt_pk_bf16_f32 v20, v20, v21
	v_cvt_pk_bf16_f32 v21, v22, v23
	v_cvt_pk_bf16_f32 v22, v12, v13
	v_lshl_add_u64 v[12:13], s[0:1], 0, v[168:169]
	v_cvt_pk_bf16_f32 v23, v14, v15
	global_store_dwordx4 v[12:13], v[20:23], off sc1
	v_cvt_pk_bf16_f32 v12, v16, v17
	v_cvt_pk_bf16_f32 v13, v18, v19
	v_cvt_pk_bf16_f32 v14, v8, v9
	v_lshl_add_u64 v[8:9], s[66:67], 0, v[170:171]
	v_cvt_pk_bf16_f32 v15, v10, v11
	global_store_dwordx4 v[8:9], v[12:15], off sc1
	v_cvt_pk_bf16_f32 v4, v4, v5
	v_cvt_pk_bf16_f32 v5, v6, v7
	v_cvt_pk_bf16_f32 v6, v0, v1
	v_lshl_add_u64 v[0:1], s[0:1], 0, v[170:171]
	s_mov_b64 s[0:1], -1
	s_and_b64 vcc, exec, s[2:3]
	v_cvt_pk_bf16_f32 v7, v2, v3
	global_store_dwordx4 v[0:1], v[4:7], off sc1
	s_cbranch_vccnz .LBB0_636
	s_andn2_b64 vcc, exec, s[54:55]
	s_cbranch_vccnz .LBB0_635
	s_barrier
	s_branch .LBB0_635

; __device__ __forceinline__ float bf_lo(unsigned w) { return __uint_as_float(w << 16); }
; __device__ __forceinline__ float bf_hi(unsigned w) { return __uint_as_float(w & 0xffff0000u); }
;     __device__ static __forceinline__ float ub(unsigned w, int k) { return (float)((w >> (8 * k)) & 0xffu); }
; #define PG8_BAR __builtin_amdgcn_s_barrier()
;     __device__ __forceinline__ void operator()(f32x4 (&acc)[2][2][4][2], const Unit& u, int wr, int wc, int fr, int fq) const {
;     ...
;             for (int m = 0; m < 4; ++m) gw[ai][m] = *(const u32x4*)(G8 + ((size_t)(((u.pm * 8 + gsel + u.pn) * 8 + (wr * 4 + wc)) * 8 + (ai * 4 + m)) * 1024) + (fq * 16 + fr) * 16);
;         if (ACCUM) {
;             int chain = row0; float dep = acc[0][0][0][0][0];
; #pragma unroll
;             for (int ai = 0; ai < 2; ++ai) { u32x4 ow[4][2];
;                 asm volatile("" : "+v"(chain) : "v"(dep));
; #pragma unroll
;                 for (int m = 0; m < 4; ++m)
; #pragma unroll
;                     for (int bj = 0; bj < 2; ++bj) ow[m][bj] = *(const u32x4*)(mg_at(u, ai, m, bj, wr, wc, fr, fq) + (chain - row0));
; #pragma unroll
;                 for (int m = 0; m < 4; ++m)
; #pragma unroll
;                     for (int bj = 0; bj < 2; ++bj) { const u32x4 gq = gw[ai][m]; u32x2 g; g.x = bj ? gq.z : gq.x; g.y = bj ? gq.w : gq.y; const u32x4 o = ow[m][bj]; f32x4& a0 = acc[ai][bj][m][0]; f32x4& a1 = acc[ai][bj][m][1];
;                         a0[0] = a0[0] * (ub(g.x, 0) * q) + bf_lo(o.x); a0[1] = a0[1] * (ub(g.x, 1) * q) + bf_hi(o.x); a0[2] = a0[2] * (ub(g.x, 2) * q) + bf_lo(o.y); a0[3] = a0[3] * (ub(g.x, 3) * q) + bf_hi(o.y);
;                         a1[0] = a1[0] * (ub(g.y, 0) * q) + bf_lo(o.z); a1[1] = a1[1] * (ub(g.y, 1) * q) + bf_hi(o.z); a1[2] = a1[2] * (ub(g.y, 2) * q) + bf_lo(o.w); a1[3] = a1[3] * (ub(g.y, 3) * q) + bf_hi(o.w);
; template <class Epi, class Sched, bool ALIGN_EPI = false, bool SP2 = false>
; __device__ __forceinline__ void gemm_phase(PG8_LAS unsigned char* lds, const Gemm g, const Sched& S, const Epi& E) {
;     ...
;         if constexpr (ALIGN_EPI) { if (wr == 0) PG8_BAR; }
.LBB0_673:
	s_lshl_b32 s9, s63, 6
	s_lshl_b32 s8, s62, 9
	s_add_i32 s9, s77, s9
	s_add_i32 s8, s9, s8
	s_ashr_i32 s9, s8, 31
	s_lshl_b64 s[64:65], s[8:9], 10
	v_lshl_add_u64 v[108:109], v[184:185], 0, s[64:65]
	s_or_b32 s64, s8, 1
	s_ashr_i32 s65, s64, 31
	s_lshl_b64 s[64:65], s[64:65], 10
	v_lshl_add_u64 v[110:111], v[184:185], 0, s[64:65]
	s_or_b32 s64, s8, 2
	s_ashr_i32 s65, s64, 31
	s_lshl_b64 s[64:65], s[64:65], 10
	global_load_dwordx4 v[204:207], v[108:109], off
	global_load_dwordx4 v[164:167], v[110:111], off
	v_lshl_add_u64 v[108:109], v[184:185], 0, s[64:65]
	s_or_b32 s64, s8, 3
	s_ashr_i32 s65, s64, 31
	s_lshl_b64 s[64:65], s[64:65], 10
	v_lshl_add_u64 v[110:111], v[184:185], 0, s[64:65]
	s_or_b32 s64, s8, 4
	s_ashr_i32 s65, s64, 31
	s_lshl_b64 s[64:65], s[64:65], 10
	global_load_dwordx4 v[152:155], v[108:109], off
	global_load_dwordx4 v[144:147], v[110:111], off
	v_lshl_add_u64 v[108:109], v[184:185], 0, s[64:65]
	s_or_b32 s64, s8, 5
	s_ashr_i32 s65, s64, 31
	s_lshl_b64 s[64:65], s[64:65], 10
	v_lshl_add_u64 v[110:111], v[184:185], 0, s[64:65]
	s_or_b32 s64, s8, 6
	s_or_b32 s8, s8, 7
	s_ashr_i32 s65, s64, 31
	s_ashr_i32 s9, s8, 31
	s_lshl_b64 s[64:65], s[64:65], 10
	s_lshl_b64 s[8:9], s[8:9], 10
	v_lshl_add_u32 v219, s62, 8, v198
	global_load_dwordx4 v[140:143], v[108:109], off
	global_load_dwordx4 v[136:139], v[110:111], off
	v_lshl_add_u64 v[108:109], v[184:185], 0, s[64:65]
	v_lshl_add_u64 v[110:111], v[184:185], 0, s[8:9]
	s_lshl_b32 s8, s63, 3
	s_lshl_b32 s9, s62, 5
	v_mov_b32_e32 v236, v219
	global_load_dwordx4 v[132:135], v[108:109], off
	s_nop 0
	global_load_dwordx4 v[108:111], v[110:111], off
	s_add_i32 s9, s9, s8
	s_or_b32 s66, s9, s74
	v_sub_u32_e32 v148, v236, v219
	v_ashrrev_i32_e32 v149, 31, v148
	v_lshl_add_u64 v[148:149], s[6:7], 0, v[148:149]
	s_ashr_i32 s67, s66, 31
	s_lshl_b64 s[64:65], s[66:67], 14
	v_lshl_add_u64 v[150:151], v[148:149], 0, v[176:177]
	v_lshl_add_u64 v[156:157], v[150:151], 0, s[64:65]
	global_load_dwordx4 v[208:211], v[156:157], off
	s_or_b32 s8, s66, 4
	s_ashr_i32 s9, s8, 31
	s_lshl_b64 s[62:63], s[8:9], 14
	v_lshl_add_u64 v[150:151], v[150:151], 0, s[62:63]
	global_load_dwordx4 v[212:215], v[150:151], off
	v_lshl_add_u64 v[150:151], v[148:149], 0, v[178:179]
	v_lshl_add_u64 v[156:157], v[150:151], 0, s[64:65]
	global_load_dwordx4 v[220:223], v[156:157], off
	v_lshl_add_u64 v[156:157], v[148:149], 0, v[180:181]
	v_lshl_add_u64 v[148:149], v[148:149], 0, v[182:183]
	v_lshl_add_u64 v[150:151], v[150:151], 0, s[62:63]
	v_lshl_add_u64 v[158:159], v[156:157], 0, s[64:65]
	v_lshl_add_u64 v[156:157], v[156:157], 0, s[62:63]
	v_lshl_add_u64 v[216:217], v[148:149], 0, s[64:65]
	v_lshl_add_u64 v[148:149], v[148:149], 0, s[62:63]
	global_load_dwordx4 v[224:227], v[150:151], off
	global_load_dwordx4 v[168:171], v[158:159], off
	global_load_dwordx4 v[160:163], v[156:157], off
	s_nop 0
	global_load_dwordx4 v[156:159], v[216:217], off
	s_nop 0
	global_load_dwordx4 v[148:151], v[148:149], off
	s_or_b32 s8, s66, 1
	s_ashr_i32 s9, s8, 31
	s_lshl_b64 s[68:69], s[8:9], 14
	s_or_b32 s8, s66, 5
	s_ashr_i32 s9, s8, 31
	s_lshl_b64 s[66:67], s[8:9], 14
	s_add_u32 s64, s6, s64
	s_addc_u32 s65, s7, s65
	s_add_u32 s62, s6, s62
	s_addc_u32 s63, s7, s63
	v_readlane_b32 s99, v246, 6
	s_nop 1
	s_cmp_lt_u32 s99, 4
	s_cbranch_scc0 .Lnoal_4
	s_barrier
.Lnoal_4:
	s_waitcnt vmcnt(0)
	v_cvt_f32_ubyte3_e32 v229, v204
	v_cvt_f32_ubyte2_e32 v228, v204
	v_pk_mul_f32 v[228:229], v[228:229], s[10:11] op_sel_hi:[1,0]
	v_cvt_f32_ubyte1_e32 v217, v204
	v_cvt_f32_ubyte0_e32 v216, v204
	v_cvt_f32_ubyte1_e32 v231, v205
	v_cvt_f32_ubyte0_e32 v230, v205
	v_pk_mul_f32 v[216:217], v[216:217], s[10:11] op_sel_hi:[1,0]
	v_pk_mul_f32 v[230:231], v[230:231], s[10:11] op_sel_hi:[1,0]
	v_lshlrev_b32_e32 v232, 16, v208
	v_and_b32_e32 v233, 0xffff0000, v208
	v_lshlrev_b32_e32 v208, 16, v209
	v_and_b32_e32 v209, 0xffff0000, v209
	v_pk_fma_f32 v[130:131], v[130:131], v[228:229], v[208:209]
	v_cvt_f32_ubyte3_e32 v209, v205
	v_cvt_f32_ubyte2_e32 v208, v205
	v_pk_mul_f32 v[204:205], v[208:209], s[10:11] op_sel_hi:[1,0]
	v_lshlrev_b32_e32 v208, 16, v211
	v_and_b32_e32 v209, 0xffff0000, v211
	v_pk_fma_f32 v[126:127], v[126:127], v[204:205], v[208:209]
	v_cvt_f32_ubyte1_e32 v205, v206
	v_cvt_f32_ubyte0_e32 v204, v206
	v_pk_mul_f32 v[204:205], v[204:205], s[10:11] op_sel_hi:[1,0]
	v_lshlrev_b32_e32 v208, 16, v212
	v_and_b32_e32 v209, 0xffff0000, v212
	v_pk_fma_f32 v[120:121], v[120:121], v[204:205], v[208:209]
	v_cvt_f32_ubyte3_e32 v205, v206
	v_cvt_f32_ubyte2_e32 v204, v206
	v_pk_mul_f32 v[204:205], v[204:205], s[10:11] op_sel_hi:[1,0]
	v_lshlrev_b32_e32 v208, 16, v213
	v_and_b32_e32 v209, 0xffff0000, v213
	v_pk_fma_f32 v[122:123], v[122:123], v[204:205], v[208:209]
	v_cvt_f32_ubyte1_e32 v205, v207
	v_cvt_f32_ubyte0_e32 v204, v207
	v_pk_mul_f32 v[204:205], v[204:205], s[10:11] op_sel_hi:[1,0]
	v_lshlrev_b32_e32 v208, 16, v214
	v_and_b32_e32 v209, 0xffff0000, v214
	v_pk_fma_f32 v[116:117], v[116:117], v[204:205], v[208:209]
	v_cvt_f32_ubyte3_e32 v205, v207
	v_cvt_f32_ubyte2_e32 v204, v207
	v_pk_mul_f32 v[204:205], v[204:205], s[10:11] op_sel_hi:[1,0]
	v_lshlrev_b32_e32 v206, 16, v215
	v_and_b32_e32 v207, 0xffff0000, v215
	v_pk_fma_f32 v[118:119], v[118:119], v[204:205], v[206:207]
	v_cvt_f32_ubyte1_e32 v205, v164
	v_cvt_f32_ubyte0_e32 v204, v164
	v_pk_mul_f32 v[204:205], v[204:205], s[10:11] op_sel_hi:[1,0]
	v_lshlrev_b32_e32 v206, 16, v220
	v_and_b32_e32 v207, 0xffff0000, v220
	v_pk_fma_f32 v[112:113], v[112:113], v[204:205], v[206:207]
	v_cvt_f32_ubyte3_e32 v205, v164
	v_cvt_f32_ubyte2_e32 v204, v164
	v_pk_mul_f32 v[204:205], v[204:205], s[10:11] op_sel_hi:[1,0]
; __device__ __forceinline__ float bf_lo(unsigned w) { return __uint_as_float(w << 16); }
; __device__ __forceinline__ float bf_hi(unsigned w) { return __uint_as_float(w & 0xffff0000u); }
;     __device__ static __forceinline__ float ub(unsigned w, int k) { return (float)((w >> (8 * k)) & 0xffu); }
;     __device__ __forceinline__ void operator()(f32x4 (&acc)[2][2][4][2], const Unit& u, int wr, int wc, int fr, int fq) const {
;     ...
;                     for (int bj = 0; bj < 2; ++bj) { const u32x4 gq = gw[ai][m]; u32x2 g; g.x = bj ? gq.z : gq.x; g.y = bj ? gq.w : gq.y; const u32x4 o = ow[m][bj]; f32x4& a0 = acc[ai][bj][m][0]; f32x4& a1 = acc[ai][bj][m][1];
;                         a0[0] = a0[0] * (ub(g.x, 0) * q) + bf_lo(o.x); a0[1] = a0[1] * (ub(g.x, 1) * q) + bf_hi(o.x); a0[2] = a0[2] * (ub(g.x, 2) * q) + bf_lo(o.y); a0[3] = a0[3] * (ub(g.x, 3) * q) + bf_hi(o.y);
;                         a1[0] = a1[0] * (ub(g.y, 0) * q) + bf_lo(o.z); a1[1] = a1[1] * (ub(g.y, 1) * q) + bf_hi(o.z); a1[2] = a1[2] * (ub(g.y, 2) * q) + bf_lo(o.w); a1[3] = a1[3] * (ub(g.y, 3) * q) + bf_hi(o.w);
	v_lshlrev_b32_e32 v206, 16, v221
	v_and_b32_e32 v207, 0xffff0000, v221
	v_pk_fma_f32 v[114:115], v[114:115], v[204:205], v[206:207]
	v_cvt_f32_ubyte1_e32 v205, v165
	v_cvt_f32_ubyte0_e32 v204, v165
	v_pk_mul_f32 v[204:205], v[204:205], s[10:11] op_sel_hi:[1,0]
	v_lshlrev_b32_e32 v206, 16, v222
	v_and_b32_e32 v207, 0xffff0000, v222
	v_pk_fma_f32 v[104:105], v[104:105], v[204:205], v[206:207]
	v_cvt_f32_ubyte3_e32 v205, v165
	v_cvt_f32_ubyte2_e32 v204, v165
	v_pk_mul_f32 v[164:165], v[204:205], s[10:11] op_sel_hi:[1,0]
	v_lshlrev_b32_e32 v204, 16, v223
	v_and_b32_e32 v205, 0xffff0000, v223
	v_pk_fma_f32 v[106:107], v[106:107], v[164:165], v[204:205]
	v_cvt_f32_ubyte1_e32 v165, v166
	v_cvt_f32_ubyte0_e32 v164, v166
	v_pk_mul_f32 v[164:165], v[164:165], s[10:11] op_sel_hi:[1,0]
	v_lshlrev_b32_e32 v204, 16, v224
	v_and_b32_e32 v205, 0xffff0000, v224
	v_pk_fma_f32 v[100:101], v[100:101], v[164:165], v[204:205]
	v_cvt_f32_ubyte3_e32 v165, v166
	v_cvt_f32_ubyte2_e32 v164, v166
	v_pk_mul_f32 v[164:165], v[164:165], s[10:11] op_sel_hi:[1,0]
	v_lshlrev_b32_e32 v204, 16, v225
	v_and_b32_e32 v205, 0xffff0000, v225
	v_pk_fma_f32 v[102:103], v[102:103], v[164:165], v[204:205]
	v_cvt_f32_ubyte1_e32 v165, v167
	v_cvt_f32_ubyte0_e32 v164, v167
	v_pk_mul_f32 v[164:165], v[164:165], s[10:11] op_sel_hi:[1,0]
	v_lshlrev_b32_e32 v204, 16, v226
	v_and_b32_e32 v205, 0xffff0000, v226
	v_pk_fma_f32 v[96:97], v[96:97], v[164:165], v[204:205]
	v_cvt_f32_ubyte3_e32 v165, v167
	v_cvt_f32_ubyte2_e32 v164, v167
	v_pk_mul_f32 v[164:165], v[164:165], s[10:11] op_sel_hi:[1,0]
	v_lshlrev_b32_e32 v166, 16, v227
	v_and_b32_e32 v167, 0xffff0000, v227
	v_pk_fma_f32 v[98:99], v[98:99], v[164:165], v[166:167]
	v_cvt_f32_ubyte1_e32 v165, v152
	v_cvt_f32_ubyte0_e32 v164, v152
	v_pk_mul_f32 v[164:165], v[164:165], s[10:11] op_sel_hi:[1,0]
	v_lshlrev_b32_e32 v166, 16, v168
	v_and_b32_e32 v167, 0xffff0000, v168
	v_pk_fma_f32 v[92:93], v[92:93], v[164:165], v[166:167]
	v_cvt_f32_ubyte3_e32 v165, v152
	v_cvt_f32_ubyte2_e32 v164, v152
	v_pk_mul_f32 v[164:165], v[164:165], s[10:11] op_sel_hi:[1,0]
	v_lshlrev_b32_e32 v166, 16, v169
	v_and_b32_e32 v167, 0xffff0000, v169
	v_pk_fma_f32 v[94:95], v[94:95], v[164:165], v[166:167]
	v_cvt_f32_ubyte1_e32 v165, v153
	v_cvt_f32_ubyte0_e32 v164, v153
	v_pk_mul_f32 v[164:165], v[164:165], s[10:11] op_sel_hi:[1,0]
	v_lshlrev_b32_e32 v166, 16, v170
	v_and_b32_e32 v167, 0xffff0000, v170
	v_pk_fma_f32 v[88:89], v[88:89], v[164:165], v[166:167]
	v_cvt_f32_ubyte3_e32 v165, v153
	v_cvt_f32_ubyte2_e32 v164, v153
	v_pk_mul_f32 v[152:153], v[164:165], s[10:11] op_sel_hi:[1,0]
	v_lshlrev_b32_e32 v164, 16, v171
	v_and_b32_e32 v165, 0xffff0000, v171
	v_pk_fma_f32 v[90:91], v[90:91], v[152:153], v[164:165]
	v_cvt_f32_ubyte1_e32 v153, v154
	v_cvt_f32_ubyte0_e32 v152, v154
	v_pk_mul_f32 v[152:153], v[152:153], s[10:11] op_sel_hi:[1,0]
	v_lshlrev_b32_e32 v164, 16, v160
	v_and_b32_e32 v165, 0xffff0000, v160
	v_pk_fma_f32 v[84:85], v[84:85], v[152:153], v[164:165]
	v_cvt_f32_ubyte3_e32 v153, v154
	v_cvt_f32_ubyte2_e32 v152, v154
	v_pk_mul_f32 v[152:153], v[152:153], s[10:11] op_sel_hi:[1,0]
	v_lshlrev_b32_e32 v160, 16, v161
	v_and_b32_e32 v161, 0xffff0000, v161
	v_pk_fma_f32 v[86:87], v[86:87], v[152:153], v[160:161]
	v_cvt_f32_ubyte1_e32 v153, v155
	v_cvt_f32_ubyte0_e32 v152, v155
	v_pk_mul_f32 v[152:153], v[152:153], s[10:11] op_sel_hi:[1,0]
	v_lshlrev_b32_e32 v160, 16, v162
	v_and_b32_e32 v161, 0xffff0000, v162
	v_pk_fma_f32 v[80:81], v[80:81], v[152:153], v[160:161]
	v_cvt_f32_ubyte3_e32 v153, v155
	v_cvt_f32_ubyte2_e32 v152, v155
	v_pk_mul_f32 v[152:153], v[152:153], s[10:11] op_sel_hi:[1,0]
	v_lshlrev_b32_e32 v154, 16, v163
	v_and_b32_e32 v155, 0xffff0000, v163
	v_pk_fma_f32 v[82:83], v[82:83], v[152:153], v[154:155]
	v_cvt_f32_ubyte1_e32 v153, v144
	v_cvt_f32_ubyte0_e32 v152, v144
	v_pk_mul_f32 v[152:153], v[152:153], s[10:11] op_sel_hi:[1,0]
	v_lshlrev_b32_e32 v154, 16, v156
	v_and_b32_e32 v155, 0xffff0000, v156
	v_pk_fma_f32 v[76:77], v[76:77], v[152:153], v[154:155]
	v_cvt_f32_ubyte3_e32 v153, v144
	v_cvt_f32_ubyte2_e32 v152, v144
	v_pk_mul_f32 v[152:153], v[152:153], s[10:11] op_sel_hi:[1,0]
	v_lshlrev_b32_e32 v154, 16, v157
	v_and_b32_e32 v155, 0xffff0000, v157
	v_pk_fma_f32 v[78:79], v[78:79], v[152:153], v[154:155]
	v_cvt_f32_ubyte1_e32 v153, v145
	v_cvt_f32_ubyte0_e32 v152, v145
	v_pk_mul_f32 v[152:153], v[152:153], s[10:11] op_sel_hi:[1,0]
	v_lshlrev_b32_e32 v154, 16, v158
	v_and_b32_e32 v155, 0xffff0000, v158
	v_pk_fma_f32 v[72:73], v[72:73], v[152:153], v[154:155]
	v_cvt_f32_ubyte3_e32 v153, v145
	v_cvt_f32_ubyte2_e32 v152, v145
	v_pk_mul_f32 v[144:145], v[152:153], s[10:11] op_sel_hi:[1,0]
	v_lshlrev_b32_e32 v152, 16, v159
	v_and_b32_e32 v153, 0xffff0000, v159
	v_pk_fma_f32 v[74:75], v[74:75], v[144:145], v[152:153]
	v_cvt_f32_ubyte1_e32 v145, v146
	v_cvt_f32_ubyte0_e32 v144, v146
	v_pk_mul_f32 v[144:145], v[144:145], s[10:11] op_sel_hi:[1,0]
	v_lshlrev_b32_e32 v152, 16, v148
	v_and_b32_e32 v153, 0xffff0000, v148
	v_pk_fma_f32 v[68:69], v[68:69], v[144:145], v[152:153]
	v_cvt_f32_ubyte3_e32 v145, v146
	v_cvt_f32_ubyte2_e32 v144, v146
	v_pk_mul_f32 v[144:145], v[144:145], s[10:11] op_sel_hi:[1,0]
	v_lshlrev_b32_e32 v148, 16, v149
	v_and_b32_e32 v149, 0xffff0000, v149
	v_pk_fma_f32 v[70:71], v[70:71], v[144:145], v[148:149]
	v_cvt_f32_ubyte1_e32 v145, v147
	v_cvt_f32_ubyte0_e32 v144, v147
	v_pk_mul_f32 v[144:145], v[144:145], s[10:11] op_sel_hi:[1,0]
	v_lshlrev_b32_e32 v148, 16, v150
	v_and_b32_e32 v149, 0xffff0000, v150
	v_pk_fma_f32 v[64:65], v[64:65], v[144:145], v[148:149]
	v_cvt_f32_ubyte3_e32 v145, v147
	v_cvt_f32_ubyte2_e32 v144, v147
; __device__ __forceinline__ float bf_lo(unsigned w) { return __uint_as_float(w << 16); }
; __device__ __forceinline__ float bf_hi(unsigned w) { return __uint_as_float(w & 0xffff0000u); }
;     __device__ static __forceinline__ float ub(unsigned w, int k) { return (float)((w >> (8 * k)) & 0xffu); }
;     __device__ __forceinline__ void operator()(f32x4 (&acc)[2][2][4][2], const Unit& u, int wr, int wc, int fr, int fq) const {
;     ...
;             for (int ai = 0; ai < 2; ++ai) { u32x4 ow[4][2];
;                 asm volatile("" : "+v"(chain) : "v"(dep));
; #pragma unroll
;                 for (int m = 0; m < 4; ++m)
; #pragma unroll
;                     for (int bj = 0; bj < 2; ++bj) ow[m][bj] = *(const u32x4*)(mg_at(u, ai, m, bj, wr, wc, fr, fq) + (chain - row0));
; #pragma unroll
;                 for (int m = 0; m < 4; ++m)
; #pragma unroll
;                     for (int bj = 0; bj < 2; ++bj) { const u32x4 gq = gw[ai][m]; u32x2 g; g.x = bj ? gq.z : gq.x; g.y = bj ? gq.w : gq.y; const u32x4 o = ow[m][bj]; f32x4& a0 = acc[ai][bj][m][0]; f32x4& a1 = acc[ai][bj][m][1];
;                         a0[0] = a0[0] * (ub(g.x, 0) * q) + bf_lo(o.x); a0[1] = a0[1] * (ub(g.x, 1) * q) + bf_hi(o.x); a0[2] = a0[2] * (ub(g.x, 2) * q) + bf_lo(o.y); a0[3] = a0[3] * (ub(g.x, 3) * q) + bf_hi(o.y);
;                         a1[0] = a1[0] * (ub(g.y, 0) * q) + bf_lo(o.z); a1[1] = a1[1] * (ub(g.y, 1) * q) + bf_hi(o.z); a1[2] = a1[2] * (ub(g.y, 2) * q) + bf_lo(o.w); a1[3] = a1[3] * (ub(g.y, 3) * q) + bf_hi(o.w);
	v_lshlrev_b32_e32 v234, 16, v210
	v_and_b32_e32 v235, 0xffff0000, v210
	v_pk_mul_f32 v[144:145], v[144:145], s[10:11] op_sel_hi:[1,0]
	v_lshlrev_b32_e32 v146, 16, v151
	v_and_b32_e32 v147, 0xffff0000, v151
	v_pk_fma_f32 v[128:129], v[128:129], v[216:217], v[232:233]
	v_pk_fma_f32 v[124:125], v[124:125], v[230:231], v[234:235]
	v_pk_fma_f32 v[66:67], v[66:67], v[144:145], v[146:147]
	s_nop 0
	v_cvt_f32_ubyte1_e32 v209, v140
	v_cvt_f32_ubyte0_e32 v208, v140
	v_sub_u32_e32 v144, v236, v219
	v_ashrrev_i32_e32 v145, 31, v144
	v_lshl_add_u64 v[144:145], s[6:7], 0, v[144:145]
	v_lshl_add_u64 v[146:147], v[144:145], 0, v[176:177]
	v_lshl_add_u64 v[148:149], v[146:147], 0, s[68:69]
	global_load_dwordx4 v[160:163], v[148:149], off
	v_lshl_add_u64 v[146:147], v[146:147], 0, s[66:67]
	global_load_dwordx4 v[164:167], v[146:147], off
	v_lshl_add_u64 v[146:147], v[144:145], 0, v[178:179]
	v_lshl_add_u64 v[148:149], v[146:147], 0, s[68:69]
	global_load_dwordx4 v[168:171], v[148:149], off
	v_lshl_add_u64 v[146:147], v[146:147], 0, s[66:67]
	global_load_dwordx4 v[204:207], v[146:147], off
	v_lshl_add_u64 v[146:147], v[144:145], 0, v[180:181]
	v_lshl_add_u64 v[148:149], v[146:147], 0, s[68:69]
	v_lshl_add_u64 v[146:147], v[146:147], 0, s[66:67]
	global_load_dwordx4 v[156:159], v[148:149], off
	global_load_dwordx4 v[152:155], v[146:147], off
	v_lshl_add_u64 v[144:145], v[144:145], 0, v[182:183]
	v_lshl_add_u64 v[146:147], v[144:145], 0, s[68:69]
	v_lshl_add_u64 v[144:145], v[144:145], 0, s[66:67]
	global_load_dwordx4 v[148:151], v[146:147], off
	s_nop 0
	global_load_dwordx4 v[144:147], v[144:145], off
	v_pk_mul_f32 v[208:209], v[208:209], s[10:11] op_sel_hi:[1,0]
	s_waitcnt vmcnt(7)
	v_lshlrev_b32_e32 v210, 16, v160
	v_and_b32_e32 v211, 0xffff0000, v160
	v_pk_fma_f32 v[60:61], v[60:61], v[208:209], v[210:211]
	v_cvt_f32_ubyte3_e32 v209, v140
	v_cvt_f32_ubyte2_e32 v208, v140
	v_pk_mul_f32 v[208:209], v[208:209], s[10:11] op_sel_hi:[1,0]
	v_lshlrev_b32_e32 v160, 16, v161
	v_and_b32_e32 v161, 0xffff0000, v161
	v_pk_fma_f32 v[62:63], v[62:63], v[208:209], v[160:161]
	v_cvt_f32_ubyte1_e32 v161, v141
	v_cvt_f32_ubyte0_e32 v160, v141
	v_pk_mul_f32 v[160:161], v[160:161], s[10:11] op_sel_hi:[1,0]
	v_lshlrev_b32_e32 v208, 16, v162
	v_and_b32_e32 v209, 0xffff0000, v162
	v_pk_fma_f32 v[56:57], v[56:57], v[160:161], v[208:209]
	v_cvt_f32_ubyte3_e32 v161, v141
	v_cvt_f32_ubyte2_e32 v160, v141
	v_pk_mul_f32 v[140:141], v[160:161], s[10:11] op_sel_hi:[1,0]
	v_lshlrev_b32_e32 v160, 16, v163
	v_and_b32_e32 v161, 0xffff0000, v163
	v_pk_fma_f32 v[58:59], v[58:59], v[140:141], v[160:161]
	v_cvt_f32_ubyte1_e32 v141, v142
	v_cvt_f32_ubyte0_e32 v140, v142
	v_pk_mul_f32 v[140:141], v[140:141], s[10:11] op_sel_hi:[1,0]
	s_waitcnt vmcnt(6)
	v_lshlrev_b32_e32 v160, 16, v164
	v_and_b32_e32 v161, 0xffff0000, v164
	v_pk_fma_f32 v[52:53], v[52:53], v[140:141], v[160:161]
	v_cvt_f32_ubyte3_e32 v141, v142
	v_cvt_f32_ubyte2_e32 v140, v142
	v_pk_mul_f32 v[140:141], v[140:141], s[10:11] op_sel_hi:[1,0]
	v_lshlrev_b32_e32 v160, 16, v165
	v_and_b32_e32 v161, 0xffff0000, v165
	v_pk_fma_f32 v[54:55], v[54:55], v[140:141], v[160:161]
	v_cvt_f32_ubyte1_e32 v141, v143
	v_cvt_f32_ubyte0_e32 v140, v143
	v_pk_mul_f32 v[140:141], v[140:141], s[10:11] op_sel_hi:[1,0]
	v_lshlrev_b32_e32 v160, 16, v166
	v_and_b32_e32 v161, 0xffff0000, v166
	v_pk_fma_f32 v[48:49], v[48:49], v[140:141], v[160:161]
	v_cvt_f32_ubyte3_e32 v141, v143
	v_cvt_f32_ubyte2_e32 v140, v143
	v_pk_mul_f32 v[140:141], v[140:141], s[10:11] op_sel_hi:[1,0]
	v_lshlrev_b32_e32 v142, 16, v167
	v_and_b32_e32 v143, 0xffff0000, v167
	v_pk_fma_f32 v[50:51], v[50:51], v[140:141], v[142:143]
	v_cvt_f32_ubyte1_e32 v141, v136
	v_cvt_f32_ubyte0_e32 v140, v136
	v_pk_mul_f32 v[140:141], v[140:141], s[10:11] op_sel_hi:[1,0]
	s_waitcnt vmcnt(5)
	v_lshlrev_b32_e32 v142, 16, v168
	v_and_b32_e32 v143, 0xffff0000, v168
	v_pk_fma_f32 v[44:45], v[44:45], v[140:141], v[142:143]
	v_cvt_f32_ubyte3_e32 v141, v136
	v_cvt_f32_ubyte2_e32 v140, v136
	v_pk_mul_f32 v[140:141], v[140:141], s[10:11] op_sel_hi:[1,0]
	v_lshlrev_b32_e32 v142, 16, v169
	v_and_b32_e32 v143, 0xffff0000, v169
	v_pk_fma_f32 v[46:47], v[46:47], v[140:141], v[142:143]
	v_cvt_f32_ubyte1_e32 v141, v137
	v_cvt_f32_ubyte0_e32 v140, v137
	v_pk_mul_f32 v[140:141], v[140:141], s[10:11] op_sel_hi:[1,0]
	v_lshlrev_b32_e32 v142, 16, v170
	v_and_b32_e32 v143, 0xffff0000, v170
	v_pk_fma_f32 v[40:41], v[40:41], v[140:141], v[142:143]
	v_cvt_f32_ubyte3_e32 v141, v137
	v_cvt_f32_ubyte2_e32 v140, v137
	v_pk_mul_f32 v[136:137], v[140:141], s[10:11] op_sel_hi:[1,0]
	v_lshlrev_b32_e32 v140, 16, v171
	v_and_b32_e32 v141, 0xffff0000, v171
	v_pk_fma_f32 v[42:43], v[42:43], v[136:137], v[140:141]
	v_cvt_f32_ubyte1_e32 v137, v138
	v_cvt_f32_ubyte0_e32 v136, v138
	v_pk_mul_f32 v[136:137], v[136:137], s[10:11] op_sel_hi:[1,0]
	s_waitcnt vmcnt(4)
	v_lshlrev_b32_e32 v140, 16, v204
	v_and_b32_e32 v141, 0xffff0000, v204
	v_pk_fma_f32 v[36:37], v[36:37], v[136:137], v[140:141]
	v_cvt_f32_ubyte3_e32 v137, v138
	v_cvt_f32_ubyte2_e32 v136, v138
	v_pk_mul_f32 v[136:137], v[136:137], s[10:11] op_sel_hi:[1,0]
	v_lshlrev_b32_e32 v140, 16, v205
	v_and_b32_e32 v141, 0xffff0000, v205
	v_pk_fma_f32 v[38:39], v[38:39], v[136:137], v[140:141]
	v_cvt_f32_ubyte1_e32 v137, v139
	v_cvt_f32_ubyte0_e32 v136, v139
	v_pk_mul_f32 v[136:137], v[136:137], s[10:11] op_sel_hi:[1,0]
	v_lshlrev_b32_e32 v140, 16, v206
	v_and_b32_e32 v141, 0xffff0000, v206
	v_pk_fma_f32 v[32:33], v[32:33], v[136:137], v[140:141]
	v_cvt_f32_ubyte3_e32 v137, v139
	v_cvt_f32_ubyte2_e32 v136, v139
	v_pk_mul_f32 v[136:137], v[136:137], s[10:11] op_sel_hi:[1,0]
	v_lshlrev_b32_e32 v138, 16, v207
	v_and_b32_e32 v139, 0xffff0000, v207
	v_pk_fma_f32 v[34:35], v[34:35], v[136:137], v[138:139]
	v_cvt_f32_ubyte1_e32 v137, v132
	v_cvt_f32_ubyte0_e32 v136, v132
	v_pk_mul_f32 v[136:137], v[136:137], s[10:11] op_sel_hi:[1,0]
	s_waitcnt vmcnt(3)
; __device__ __forceinline__ float bf_lo(unsigned w) { return __uint_as_float(w << 16); }
; __device__ __forceinline__ float bf_hi(unsigned w) { return __uint_as_float(w & 0xffff0000u); }
;     __device__ static __forceinline__ float ub(unsigned w, int k) { return (float)((w >> (8 * k)) & 0xffu); }
;     __device__ __forceinline__ void operator()(f32x4 (&acc)[2][2][4][2], const Unit& u, int wr, int wc, int fr, int fq) const {
;     ...
;                 for (int m = 0; m < 4; ++m)
; #pragma unroll
;                     for (int bj = 0; bj < 2; ++bj) { const u32x4 gq = gw[ai][m]; u32x2 g; g.x = bj ? gq.z : gq.x; g.y = bj ? gq.w : gq.y; const u32x4 o = ow[m][bj]; f32x4& a0 = acc[ai][bj][m][0]; f32x4& a1 = acc[ai][bj][m][1];
;                         a0[0] = a0[0] * (ub(g.x, 0) * q) + bf_lo(o.x); a0[1] = a0[1] * (ub(g.x, 1) * q) + bf_hi(o.x); a0[2] = a0[2] * (ub(g.x, 2) * q) + bf_lo(o.y); a0[3] = a0[3] * (ub(g.x, 3) * q) + bf_hi(o.y);
;                         a1[0] = a1[0] * (ub(g.y, 0) * q) + bf_lo(o.z); a1[1] = a1[1] * (ub(g.y, 1) * q) + bf_hi(o.z); a1[2] = a1[2] * (ub(g.y, 2) * q) + bf_lo(o.w); a1[3] = a1[3] * (ub(g.y, 3) * q) + bf_hi(o.w);
	v_lshlrev_b32_e32 v138, 16, v156
	v_and_b32_e32 v139, 0xffff0000, v156
	v_pk_fma_f32 v[28:29], v[28:29], v[136:137], v[138:139]
	v_cvt_f32_ubyte3_e32 v137, v132
	v_cvt_f32_ubyte2_e32 v136, v132
	v_pk_mul_f32 v[136:137], v[136:137], s[10:11] op_sel_hi:[1,0]
	v_lshlrev_b32_e32 v138, 16, v157
	v_and_b32_e32 v139, 0xffff0000, v157
	v_pk_fma_f32 v[30:31], v[30:31], v[136:137], v[138:139]
	v_cvt_f32_ubyte1_e32 v137, v133
	v_cvt_f32_ubyte0_e32 v136, v133
	v_pk_mul_f32 v[136:137], v[136:137], s[10:11] op_sel_hi:[1,0]
	v_lshlrev_b32_e32 v138, 16, v158
	v_and_b32_e32 v139, 0xffff0000, v158
	v_pk_fma_f32 v[24:25], v[24:25], v[136:137], v[138:139]
	v_cvt_f32_ubyte3_e32 v137, v133
	v_cvt_f32_ubyte2_e32 v136, v133
	v_pk_mul_f32 v[132:133], v[136:137], s[10:11] op_sel_hi:[1,0]
	v_lshlrev_b32_e32 v136, 16, v159
	v_and_b32_e32 v137, 0xffff0000, v159
	v_pk_fma_f32 v[26:27], v[26:27], v[132:133], v[136:137]
	v_cvt_f32_ubyte1_e32 v133, v134
	v_cvt_f32_ubyte0_e32 v132, v134
	v_pk_mul_f32 v[132:133], v[132:133], s[10:11] op_sel_hi:[1,0]
	s_waitcnt vmcnt(2)
	v_lshlrev_b32_e32 v136, 16, v152
	v_and_b32_e32 v137, 0xffff0000, v152
	v_pk_fma_f32 v[20:21], v[20:21], v[132:133], v[136:137]
	v_cvt_f32_ubyte3_e32 v133, v134
	v_cvt_f32_ubyte2_e32 v132, v134
	v_pk_mul_f32 v[132:133], v[132:133], s[10:11] op_sel_hi:[1,0]
	v_lshlrev_b32_e32 v136, 16, v153
	v_and_b32_e32 v137, 0xffff0000, v153
	v_pk_fma_f32 v[22:23], v[22:23], v[132:133], v[136:137]
	v_cvt_f32_ubyte1_e32 v133, v135
	v_cvt_f32_ubyte0_e32 v132, v135
	v_pk_mul_f32 v[132:133], v[132:133], s[10:11] op_sel_hi:[1,0]
	v_lshlrev_b32_e32 v136, 16, v154
	v_and_b32_e32 v137, 0xffff0000, v154
	v_pk_fma_f32 v[16:17], v[16:17], v[132:133], v[136:137]
	v_cvt_f32_ubyte3_e32 v133, v135
	v_cvt_f32_ubyte2_e32 v132, v135
	v_pk_mul_f32 v[132:133], v[132:133], s[10:11] op_sel_hi:[1,0]
	v_lshlrev_b32_e32 v134, 16, v155
	v_and_b32_e32 v135, 0xffff0000, v155
	v_pk_fma_f32 v[18:19], v[18:19], v[132:133], v[134:135]
	v_cvt_f32_ubyte1_e32 v133, v108
	v_cvt_f32_ubyte0_e32 v132, v108
	v_pk_mul_f32 v[132:133], v[132:133], s[10:11] op_sel_hi:[1,0]
	s_waitcnt vmcnt(1)
	v_lshlrev_b32_e32 v134, 16, v148
	v_and_b32_e32 v135, 0xffff0000, v148
	v_pk_fma_f32 v[12:13], v[12:13], v[132:133], v[134:135]
	v_cvt_f32_ubyte3_e32 v133, v108
	v_cvt_f32_ubyte2_e32 v132, v108
	v_pk_mul_f32 v[132:133], v[132:133], s[10:11] op_sel_hi:[1,0]
	v_lshlrev_b32_e32 v134, 16, v149
	v_and_b32_e32 v135, 0xffff0000, v149
	v_pk_fma_f32 v[14:15], v[14:15], v[132:133], v[134:135]
	v_cvt_f32_ubyte1_e32 v133, v109
	v_cvt_f32_ubyte0_e32 v132, v109
	v_pk_mul_f32 v[132:133], v[132:133], s[10:11] op_sel_hi:[1,0]
	v_lshlrev_b32_e32 v134, 16, v150
	v_and_b32_e32 v135, 0xffff0000, v150
	v_pk_fma_f32 v[8:9], v[8:9], v[132:133], v[134:135]
	v_cvt_f32_ubyte3_e32 v133, v109
	v_cvt_f32_ubyte2_e32 v132, v109
	v_pk_mul_f32 v[108:109], v[132:133], s[10:11] op_sel_hi:[1,0]
	v_lshlrev_b32_e32 v132, 16, v151
	v_and_b32_e32 v133, 0xffff0000, v151
	v_pk_fma_f32 v[10:11], v[10:11], v[108:109], v[132:133]
	v_cvt_f32_ubyte1_e32 v109, v110
	v_cvt_f32_ubyte0_e32 v108, v110
	v_pk_mul_f32 v[108:109], v[108:109], s[10:11] op_sel_hi:[1,0]
	s_waitcnt vmcnt(0)
; __device__ __forceinline__ unsigned cvt_pk_bf16(float lo, float hi) { unsigned r; asm volatile("v_cvt_pk_bf16_f32 %0, %1, %2" : "=v"(r) : "v"(lo), "v"(hi)); return r; }
; __device__ __forceinline__ float bf_lo(unsigned w) { return __uint_as_float(w << 16); }
;     __device__ __forceinline__ void operator()(f32x4 (&acc)[2][2][4][2], const Unit& u, int wr, int wc, int fr, int fq) const {
;     ...
;                     for (int bj = 0; bj < 2; ++bj) { const u32x4 gq = gw[ai][m]; u32x2 g; g.x = bj ? gq.z : gq.x; g.y = bj ? gq.w : gq.y; const u32x4 o = ow[m][bj]; f32x4& a0 = acc[ai][bj][m][0]; f32x4& a1 = acc[ai][bj][m][1];
;                         a0[0] = a0[0] * (ub(g.x, 0) * q) + bf_lo(o.x); a0[1] = a0[1] * (ub(g.x, 1) * q) + bf_hi(o.x); a0[2] = a0[2] * (ub(g.x, 2) * q) + bf_lo(o.y); a0[3] = a0[3] * (ub(g.x, 3) * q) + bf_hi(o.y);
;                         a1[0] = a1[0] * (ub(g.y, 0) * q) + bf_lo(o.z); a1[1] = a1[1] * (ub(g.y, 1) * q) + bf_hi(o.z); a1[2] = a1[2] * (ub(g.y, 2) * q) + bf_lo(o.w); a1[3] = a1[3] * (ub(g.y, 3) * q) + bf_hi(o.w);
;                         asm volatile("" : "+v"(a0), "+v"(a1)); }
;                 dep = acc[ai][1][3][1][3]; }
;         } else {
; #pragma unroll
;             for (int ai = 0; ai < 2; ++ai)
; #pragma unroll
;                 for (int m = 0; m < 4; ++m)
; #pragma unroll
;                     for (int bj = 0; bj < 2; ++bj) { const u32x4 gq = gw[ai][m]; u32x2 g; g.x = bj ? gq.z : gq.x; g.y = bj ? gq.w : gq.y; f32x4& a0 = acc[ai][bj][m][0]; f32x4& a1 = acc[ai][bj][m][1];
;                         a0[0] *= ub(g.x, 0) * q; a0[1] *= ub(g.x, 1) * q; a0[2] *= ub(g.x, 2) * q; a0[3] *= ub(g.x, 3) * q; a1[0] *= ub(g.y, 0) * q; a1[1] *= ub(g.y, 1) * q; a1[2] *= ub(g.y, 2) * q; a1[3] *= ub(g.y, 3) * q;
;                         asm volatile("" : "+v"(a0), "+v"(a1)); }
;         }
; #pragma unroll
;         for (int ai = 0; ai < 2; ++ai)
; #pragma unroll
;             for (int m = 0; m < 4; ++m)
; #pragma unroll
;                 for (int bj = 0; bj < 2; ++bj) { const f32x4 a0 = acc[ai][bj][m][0], a1 = acc[ai][bj][m][1];
;                     u32x4 w; w.x = cvt_pk_bf16(a0[0], a0[1]); w.y = cvt_pk_bf16(a0[2], a0[3]); w.z = cvt_pk_bf16(a1[0], a1[1]); w.w = cvt_pk_bf16(a1[2], a1[3]);
;                     *(u32x4*)mg_at(u, ai, m, bj, wr, wc, fr, fq) = w; }
	v_lshlrev_b32_e32 v132, 16, v144
	v_and_b32_e32 v133, 0xffff0000, v144
	v_pk_fma_f32 v[4:5], v[4:5], v[108:109], v[132:133]
	v_cvt_f32_ubyte3_e32 v109, v110
	v_cvt_f32_ubyte2_e32 v108, v110
	v_pk_mul_f32 v[108:109], v[108:109], s[10:11] op_sel_hi:[1,0]
	v_lshlrev_b32_e32 v132, 16, v145
	v_and_b32_e32 v133, 0xffff0000, v145
	v_pk_fma_f32 v[6:7], v[6:7], v[108:109], v[132:133]
	v_cvt_f32_ubyte1_e32 v109, v111
	v_cvt_f32_ubyte0_e32 v108, v111
	v_pk_mul_f32 v[108:109], v[108:109], s[10:11] op_sel_hi:[1,0]
	v_lshlrev_b32_e32 v132, 16, v146
	v_and_b32_e32 v133, 0xffff0000, v146
	v_pk_fma_f32 v[0:1], v[0:1], v[108:109], v[132:133]
	v_cvt_f32_ubyte3_e32 v109, v111
	v_cvt_f32_ubyte2_e32 v108, v111
	v_pk_mul_f32 v[108:109], v[108:109], s[10:11] op_sel_hi:[1,0]
	v_lshlrev_b32_e32 v110, 16, v147
	v_and_b32_e32 v111, 0xffff0000, v147
	v_pk_fma_f32 v[2:3], v[2:3], v[108:109], v[110:111]
	s_nop 0
	v_cvt_pk_bf16_f32 v108, v128, v129
	v_cvt_pk_bf16_f32 v109, v130, v131
	v_cvt_pk_bf16_f32 v110, v124, v125
	v_lshl_add_u64 v[124:125], s[64:65], 0, v[176:177]
	v_cvt_pk_bf16_f32 v111, v126, v127
	global_store_dwordx4 v[124:125], v[108:111], off sc1
	s_nop 1
	v_cvt_pk_bf16_f32 v108, v120, v121
	v_cvt_pk_bf16_f32 v109, v122, v123
	v_cvt_pk_bf16_f32 v110, v116, v117
	v_lshl_add_u64 v[116:117], s[62:63], 0, v[176:177]
	v_cvt_pk_bf16_f32 v111, v118, v119
	global_store_dwordx4 v[116:117], v[108:111], off sc1
	s_nop 1
	v_cvt_pk_bf16_f32 v108, v112, v113
	v_cvt_pk_bf16_f32 v109, v114, v115
	v_cvt_pk_bf16_f32 v110, v104, v105
	v_lshl_add_u64 v[104:105], s[64:65], 0, v[178:179]
	v_cvt_pk_bf16_f32 v111, v106, v107
	global_store_dwordx4 v[104:105], v[108:111], off sc1
	v_cvt_pk_bf16_f32 v100, v100, v101
	v_cvt_pk_bf16_f32 v101, v102, v103
	v_cvt_pk_bf16_f32 v102, v96, v97
	v_lshl_add_u64 v[96:97], s[62:63], 0, v[178:179]
	v_cvt_pk_bf16_f32 v103, v98, v99
	global_store_dwordx4 v[96:97], v[100:103], off sc1
	v_cvt_pk_bf16_f32 v92, v92, v93
	v_cvt_pk_bf16_f32 v93, v94, v95
	v_cvt_pk_bf16_f32 v94, v88, v89
	v_lshl_add_u64 v[88:89], s[64:65], 0, v[180:181]
	v_cvt_pk_bf16_f32 v95, v90, v91
	global_store_dwordx4 v[88:89], v[92:95], off sc1
	v_cvt_pk_bf16_f32 v84, v84, v85
	v_cvt_pk_bf16_f32 v85, v86, v87
	v_cvt_pk_bf16_f32 v86, v80, v81
	v_lshl_add_u64 v[80:81], s[62:63], 0, v[180:181]
	v_cvt_pk_bf16_f32 v87, v82, v83
	global_store_dwordx4 v[80:81], v[84:87], off sc1
	v_cvt_pk_bf16_f32 v76, v76, v77
	v_cvt_pk_bf16_f32 v77, v78, v79
	v_cvt_pk_bf16_f32 v78, v72, v73
	v_lshl_add_u64 v[72:73], s[64:65], 0, v[182:183]
	v_cvt_pk_bf16_f32 v79, v74, v75
	global_store_dwordx4 v[72:73], v[76:79], off sc1
	v_cvt_pk_bf16_f32 v68, v68, v69
	v_cvt_pk_bf16_f32 v69, v70, v71
	v_cvt_pk_bf16_f32 v70, v64, v65
	v_lshl_add_u64 v[64:65], s[62:63], 0, v[182:183]
	s_add_u32 s62, s6, s68
	s_addc_u32 s63, s7, s69
	s_add_u32 s64, s6, s66
	v_cvt_pk_bf16_f32 v71, v66, v67
	global_store_dwordx4 v[64:65], v[68:71], off sc1
	v_cvt_pk_bf16_f32 v60, v60, v61
	v_cvt_pk_bf16_f32 v61, v62, v63
	v_cvt_pk_bf16_f32 v62, v56, v57
	v_lshl_add_u64 v[56:57], s[62:63], 0, v[176:177]
	s_addc_u32 s65, s7, s67
	v_cvt_pk_bf16_f32 v63, v58, v59
	global_store_dwordx4 v[56:57], v[60:63], off sc1
	v_cvt_pk_bf16_f32 v52, v52, v53
	v_cvt_pk_bf16_f32 v53, v54, v55
	v_cvt_pk_bf16_f32 v54, v48, v49
	v_lshl_add_u64 v[48:49], s[64:65], 0, v[176:177]
	v_cvt_pk_bf16_f32 v55, v50, v51
	global_store_dwordx4 v[48:49], v[52:55], off sc1
	v_cvt_pk_bf16_f32 v44, v44, v45
	v_cvt_pk_bf16_f32 v45, v46, v47
	v_cvt_pk_bf16_f32 v46, v40, v41
	v_lshl_add_u64 v[40:41], s[62:63], 0, v[178:179]
	v_cvt_pk_bf16_f32 v47, v42, v43
	global_store_dwordx4 v[40:41], v[44:47], off sc1
	v_cvt_pk_bf16_f32 v36, v36, v37
	v_cvt_pk_bf16_f32 v37, v38, v39
	v_cvt_pk_bf16_f32 v38, v32, v33
	v_lshl_add_u64 v[32:33], s[64:65], 0, v[178:179]
	v_cvt_pk_bf16_f32 v39, v34, v35
	global_store_dwordx4 v[32:33], v[36:39], off sc1
	v_cvt_pk_bf16_f32 v28, v28, v29
	v_cvt_pk_bf16_f32 v29, v30, v31
	v_cvt_pk_bf16_f32 v30, v24, v25
	v_lshl_add_u64 v[24:25], s[62:63], 0, v[180:181]
	v_cvt_pk_bf16_f32 v31, v26, v27
	global_store_dwordx4 v[24:25], v[28:31], off sc1
	v_cvt_pk_bf16_f32 v20, v20, v21
	v_cvt_pk_bf16_f32 v21, v22, v23
	v_cvt_pk_bf16_f32 v22, v16, v17
	v_lshl_add_u64 v[16:17], s[64:65], 0, v[180:181]
	v_cvt_pk_bf16_f32 v23, v18, v19
	global_store_dwordx4 v[16:17], v[20:23], off sc1
	v_cvt_pk_bf16_f32 v12, v12, v13
	v_cvt_pk_bf16_f32 v13, v14, v15
	v_cvt_pk_bf16_f32 v14, v8, v9
	v_lshl_add_u64 v[8:9], s[62:63], 0, v[182:183]
	v_cvt_pk_bf16_f32 v15, v10, v11
	global_store_dwordx4 v[8:9], v[12:15], off sc1
	v_cvt_pk_bf16_f32 v4, v4, v5
	v_cvt_pk_bf16_f32 v5, v6, v7
	v_cvt_pk_bf16_f32 v6, v0, v1
	v_lshl_add_u64 v[0:1], s[64:65], 0, v[182:183]
	s_andn2_b64 vcc, exec, s[2:3]
	s_mov_b64 s[2:3], -1
	v_cvt_pk_bf16_f32 v7, v2, v3
	global_store_dwordx4 v[0:1], v[4:7], off sc1
	s_cbranch_vccnz .LBB0_662
	s_andn2_b64 vcc, exec, s[48:49]
	s_cbranch_vccnz .LBB0_661
	s_barrier
	s_branch .LBB0_661

; __device__ __forceinline__ unsigned cvt_pk_bf16(float lo, float hi) { unsigned r; asm volatile("v_cvt_pk_bf16_f32 %0, %1, %2" : "=v"(r) : "v"(lo), "v"(hi)); return r; }
; __device__ __forceinline__ float bf_lo(unsigned w) { return __uint_as_float(w << 16); }
; __device__ __forceinline__ float bf_hi(unsigned w) { return __uint_as_float(w & 0xffff0000u); }
; #define PG8_BAR __builtin_amdgcn_s_barrier()
;     __device__ __forceinline__ void operator()(f32x4 (&acc)[2][2][4][2], const Unit& u, int wr, int wc, int fr, int fq) const {
;     ...
;                 for (int bj = 0; bj < 2; ++bj) pre[ai][m][bj] = *(const u32x4*)hb_at(u, ai, m, bj, wr, wc, fr, fq);
; #pragma unroll
;         for (int ai = 0; ai < 2; ++ai)
; #pragma unroll
;             for (int m = 0; m < 4; ++m) { const int row = row0 + ai * HALF + m * 16; float s = 0.f;
; #pragma unroll
;                 for (int bj = 0; bj < 2; ++bj) { const size_t o2 = (size_t)row * 1024 + col0 + bj * HALF; const u32x4 p = pre[ai][m][bj]; const f32x4 a0 = acc[ai][bj][m][0], a1 = acc[ai][bj][m][1];
;                     f32x4 o0, o1; o0[0] = bf_lo(p.x) + a0[0] * alpha; o0[1] = bf_hi(p.x) + a0[1] * alpha; o0[2] = bf_lo(p.y) + a0[2] * alpha; o0[3] = bf_hi(p.y) + a0[3] * alpha;
;                     o1[0] = bf_lo(p.z) + a1[0] * alpha; o1[1] = bf_hi(p.z) + a1[1] * alpha; o1[2] = bf_lo(p.w) + a1[2] * alpha; o1[3] = bf_hi(p.w) + a1[3] * alpha;
;                     s += ((o0[0] * o0[0] + o0[1] * o0[1]) + (o0[2] * o0[2] + o0[3] * o0[3])) + ((o1[0] * o1[0] + o1[1] * o1[1]) + (o1[2] * o1[2] + o1[3] * o1[3]));
;                     u32x4 w; w.x = cvt_pk_bf16(o0[0], o0[1]); w.y = cvt_pk_bf16(o0[2], o0[3]); w.z = cvt_pk_bf16(o1[0], o1[1]); w.w = cvt_pk_bf16(o1[2], o1[3]);
;                     *(u32x4*)hb_at(u, ai, m, bj, wr, wc, fr, fq) = w;
;                     if (out) { *(f32x4*)(out + o2) = o0; *(f32x4*)(out + o2 + 4) = o1; } }
;                 s += __shfl_xor(s, 16); s += __shfl_xor(s, 32);
;                 if (ssq && fq == 0) atomicAdd(ssq + row, s); }
; template <class Epi, class Sched, bool ALIGN_EPI = false, bool SP2 = false>
; __device__ __forceinline__ void gemm_phase(PG8_LAS unsigned char* lds, const Gemm g, const Sched& S, const Epi& E) {
;     ...
;         if constexpr (ALIGN_EPI) { if (wr == 0) PG8_BAR; }
.LBB0_754:
	s_lshl_b32 s57, s66, 3
	s_lshl_b32 s59, s64, 5
	s_add_i32 s59, s59, s57
	s_or_b32 s66, s59, s77
	s_ashr_i32 s67, s66, 31
	s_lshl_b64 s[68:69], s[66:67], 14
	s_or_b32 s70, s66, 4
	v_lshl_add_u64 v[128:129], v[198:199], 0, s[68:69]
	s_ashr_i32 s71, s70, 31
	global_load_dwordx4 v[220:223], v[128:129], off
	s_lshl_b64 s[70:71], s[70:71], 14
	v_lshl_add_u64 v[128:129], v[198:199], 0, s[70:71]
	global_load_dwordx4 v[224:227], v[128:129], off
	v_lshl_add_u32 v208, s64, 8, v210
	s_or_b32 s64, s66, 1
	s_or_b32 s72, s66, 5
	s_ashr_i32 s65, s64, 31
	s_ashr_i32 s73, s72, 31
	s_lshl_b64 s[66:67], s[64:65], 14
	s_lshl_b64 s[64:65], s[72:73], 14
	v_lshl_add_u64 v[128:129], v[200:201], 0, s[68:69]
	v_lshl_add_u64 v[130:131], v[202:203], 0, s[68:69]
	v_lshl_add_u64 v[132:133], v[196:197], 0, s[68:69]
	v_lshl_add_u64 v[134:135], v[200:201], 0, s[70:71]
	v_lshl_add_u64 v[136:137], v[202:203], 0, s[70:71]
	v_lshl_add_u64 v[138:139], v[196:197], 0, s[70:71]
	v_lshl_add_u64 v[140:141], v[198:199], 0, s[66:67]
	v_lshl_add_u64 v[142:143], v[198:199], 0, s[64:65]
	v_lshl_add_u64 v[144:145], v[200:201], 0, s[66:67]
	v_lshl_add_u64 v[146:147], v[200:201], 0, s[64:65]
	v_lshl_add_u64 v[228:229], v[202:203], 0, s[66:67]
	v_lshl_add_u64 v[230:231], v[202:203], 0, s[64:65]
	v_lshl_add_u64 v[232:233], v[196:197], 0, s[66:67]
	v_lshl_add_u64 v[234:235], v[196:197], 0, s[64:65]
	global_load_dwordx4 v[180:183], v[128:129], off
	global_load_dwordx4 v[176:179], v[134:135], off
	global_load_dwordx4 v[172:175], v[130:131], off
	global_load_dwordx4 v[168:171], v[136:137], off
	global_load_dwordx4 v[164:167], v[132:133], off
	global_load_dwordx4 v[160:163], v[138:139], off
	global_load_dwordx4 v[156:159], v[140:141], off
	global_load_dwordx4 v[152:155], v[142:143], off
	global_load_dwordx4 v[148:151], v[144:145], off
	s_nop 0
	global_load_dwordx4 v[144:147], v[146:147], off
	s_nop 0
	global_load_dwordx4 v[140:143], v[228:229], off
	global_load_dwordx4 v[136:139], v[230:231], off
	global_load_dwordx4 v[132:135], v[232:233], off
	global_load_dwordx4 v[128:131], v[234:235], off
	s_add_u32 s68, s12, s68
	s_addc_u32 s69, s13, s69
	v_lshl_add_u64 v[228:229], s[68:69], 0, v[186:187]
	s_add_u32 s70, s12, s70
	s_addc_u32 s71, s13, s71
	v_readlane_b32 s99, v246, 6
	s_nop 1
	s_cmp_lt_u32 s99, 4
	s_cbranch_scc0 .Lnoal_5
	s_barrier
.Lnoal_5:
	s_waitcnt vmcnt(0)
	v_lshlrev_b32_e32 v209, 16, v220
	v_and_b32_e32 v217, 0xffff0000, v220
	v_lshlrev_b32_e32 v219, 16, v221
	v_and_b32_e32 v220, 0xffff0000, v221
	v_lshlrev_b32_e32 v221, 16, v222
	v_and_b32_e32 v222, 0xffff0000, v222
	v_lshlrev_b32_e32 v230, 16, v223
	v_and_b32_e32 v223, 0xffff0000, v223
	v_add_f32_e32 v125, v125, v217
	v_add_f32_e32 v127, v127, v220
	v_add_f32_e32 v217, v121, v222
	v_add_f32_e32 v123, v123, v223
	v_add_f32_e32 v124, v124, v209
	v_add_f32_e32 v126, v126, v219
	v_add_f32_e32 v209, v120, v221
	v_add_f32_e32 v219, v122, v230
	v_lshlrev_b32_e32 v222, 16, v225
	v_and_b32_e32 v223, 0xffff0000, v225
	v_mul_f32_e32 v225, v125, v125
	v_mul_f32_e32 v230, v127, v127
	v_mul_f32_e32 v231, v217, v217
	v_mul_f32_e32 v232, v123, v123
	v_cvt_pk_bf16_f32 v120, v124, v125
	v_cvt_pk_bf16_f32 v121, v126, v127
	v_fmac_f32_e32 v225, v124, v124
	v_fmac_f32_e32 v230, v126, v126
	v_fmac_f32_e32 v231, v209, v209
	v_fmac_f32_e32 v232, v219, v219
	v_lshlrev_b32_e32 v220, 16, v224
	v_and_b32_e32 v221, 0xffff0000, v224
	v_lshlrev_b32_e32 v224, 16, v226
	v_cvt_pk_bf16_f32 v122, v209, v217
	v_cvt_pk_bf16_f32 v123, v219, v123
	global_store_dwordx4 v[228:229], v[120:123], off sc1
	v_add_f32_e32 v117, v117, v221
	v_add_f32_e32 v119, v119, v223
	v_add_f32_e32 v120, v225, v230
	v_add_f32_e32 v121, v231, v232
	v_add_f32_e32 v120, v120, v121
	v_add_f32_e32 v121, v112, v224
	v_and_b32_e32 v112, 0xffff0000, v226
	v_add_f32_e32 v113, v113, v112
	v_lshlrev_b32_e32 v112, 16, v227
	v_add_f32_e32 v114, v114, v112
	v_and_b32_e32 v112, 0xffff0000, v227
	v_add_f32_e32 v116, v116, v220
	v_add_f32_e32 v118, v118, v222
	v_add_f32_e32 v115, v115, v112
	v_mul_f32_e32 v112, v117, v117
	v_mul_f32_e32 v122, v119, v119
	v_fmac_f32_e32 v112, v116, v116
	v_fmac_f32_e32 v122, v118, v118
	v_add_f32_e32 v112, v112, v122
	v_mul_f32_e32 v122, v113, v113
	v_mul_f32_e32 v123, v115, v115
	v_fmac_f32_e32 v122, v121, v121
	v_fmac_f32_e32 v123, v114, v114
	v_add_f32_e32 v122, v122, v123
	v_add_f32_e32 v112, v112, v122
	v_cvt_pk_bf16_f32 v116, v116, v117
	v_and_b32_e32 v117, 64, v216
	v_add_f32_e32 v120, v120, v112
	v_xor_b32_e32 v112, 16, v216
	v_add_u32_e32 v122, 64, v117
	v_cmp_lt_i32_e32 vcc, v112, v122
	v_cvt_pk_bf16_f32 v117, v118, v119
	v_cvt_pk_bf16_f32 v118, v121, v113
	v_xor_b32_e32 v113, 32, v216
	v_cvt_pk_bf16_f32 v119, v114, v115
	v_ashrrev_i32_e32 v209, 31, v208
	v_cndmask_b32_e32 v112, v216, v112, vcc
	v_lshlrev_b32_e32 v112, 2, v112
	ds_bpermute_b32 v123, v112, v120
	v_cmp_lt_i32_e32 vcc, v113, v122
	s_waitcnt lgkmcnt(0)
	v_add_f32_e32 v114, v120, v123
	v_cndmask_b32_e32 v113, v216, v113, vcc
	v_lshlrev_b32_e32 v113, 2, v113
	ds_bpermute_b32 v115, v113, v114
	v_lshl_add_u64 v[120:121], s[70:71], 0, v[186:187]
	global_store_dwordx4 v[120:121], v[116:119], off sc1
	s_and_saveexec_b64 s[72:73], s[2:3]
	s_cbranch_execz .LBB0_756
	v_lshl_add_u64 v[116:117], v[208:209], 2, s[0:1]
	s_waitcnt lgkmcnt(0)
	v_add_f32_e32 v114, v114, v115
	global_atomic_add_f32 v[116:117], v114, off

; #define PG8_BAR __builtin_amdgcn_s_barrier()
;     __device__ __forceinline__ void operator()(f32x4 (&acc)[2][2][4][2], const Unit& u, int wr, int wc, int fr, int fq) const {
;     ...
;             for (int m = 0; m < 4; ++m) sq[ai][m] = ssq[row0 + ai * HALF + m * 16];
; #pragma unroll
;         for (int ai = 0; ai < 2; ++ai)
; #pragma unroll
;             for (int m = 0; m < 4; ++m) { const float ms = sq[ai][m] * (1.0f / 1024.0f) + 1e-6f, nrl = -__builtin_amdgcn_rsqf(ms) * LOG2E;
;                 float o[8];
; #pragma unroll
;                 for (int n = 0; n < 2; ++n)
; #pragma unroll
;                     for (int e = 0; e < 4; ++e) { const float a = acc[ai][0][m][n][e], bb = acc[ai][1][m][n][e];
;                         o[4 * n + e] = (a * bb) * __builtin_amdgcn_rcpf(__builtin_fmaf(__builtin_amdgcn_exp2f(a * nrl), ms, ms)); }
; template <class Epi, class Sched, bool ALIGN_EPI = false, bool SP2 = false>
; __device__ __forceinline__ void gemm_phase(PG8_LAS unsigned char* lds, const Gemm g, const Sched& S, const Epi& E) {
;     ...
;         if constexpr (ALIGN_EPI) { if (wr == 0) PG8_BAR; }
.LBB0_841:
	v_lshl_add_u32 v148, s60, 8, v140
	v_ashrrev_i32_e32 v149, 31, v148
	v_lshl_add_u64 v[148:149], v[148:149], 2, s[0:1]
	global_load_dword v147, v[148:149], off
	global_load_dword v150, v[148:149], off offset:64
	v_mul_f32_e32 v153, v108, v104
	global_load_dword v154, v[148:149], off offset:128
	global_load_dword v155, v[148:149], off offset:192
	global_load_dword v156, v[148:149], off offset:512
	global_load_dword v157, v[148:149], off offset:576
	global_load_dword v158, v[148:149], off offset:640
	global_load_dword v104, v[148:149], off offset:704
	v_mul_f32_e32 v105, v109, v105
	v_mul_f32_e32 v106, v110, v106
	v_mul_f32_e32 v96, v100, v96
	v_mul_f32_e32 v124, v116, v124
	v_mul_f32_e32 v125, v117, v125
	v_mul_f32_e32 v126, v118, v126
	v_mul_f32_e32 v127, v119, v127
	v_mul_f32_e32 v151, v112, v120
	v_mul_f32_e32 v152, v113, v121
	v_mul_f32_e32 v122, v114, v122
	v_mul_f32_e32 v123, v115, v123
	s_lshl_b32 s53, s61, 7
	s_or_b32 s53, s53, s71
	s_mul_i32 s55, s60, 44
	s_ashr_i32 s53, s53, 6
	s_add_i32 s60, s53, s55
	v_mul_f32_e32 v98, v102, v98
	s_ashr_i32 s61, s60, 31
	s_lshl_b64 s[60:61], s[60:61], 15
	s_add_u32 s60, s28, s60
	s_addc_u32 s61, s29, s61
	v_lshl_add_u64 v[120:121], s[60:61], 0, v[128:129]
	v_mul_f32_e32 v107, v111, v107
	v_mul_f32_e32 v88, v92, v88
	v_mul_f32_e32 v89, v93, v89
	v_mul_f32_e32 v90, v94, v90
	v_mul_f32_e32 v91, v95, v91
	v_mul_f32_e32 v80, v84, v80
	v_mul_f32_e32 v82, v86, v82
	v_mul_f32_e32 v72, v76, v72
	v_mul_f32_e32 v73, v77, v73
	v_mul_f32_e32 v74, v78, v74
	v_mul_f32_e32 v75, v79, v75
	v_mul_f32_e32 v64, v68, v64
	v_mul_f32_e32 v66, v70, v66
	v_mul_f32_e32 v56, v60, v56
	v_mul_f32_e32 v57, v61, v57
	v_mul_f32_e32 v58, v62, v58
	v_mul_f32_e32 v59, v63, v59
	v_mul_f32_e32 v48, v52, v48
	v_mul_f32_e32 v50, v54, v50
	v_mul_f32_e32 v40, v44, v40
	v_mul_f32_e32 v41, v45, v41
	v_mul_f32_e32 v42, v46, v42
	v_mul_f32_e32 v43, v47, v43
	v_mul_f32_e32 v32, v36, v32
	v_mul_f32_e32 v34, v38, v34
	v_mul_f32_e32 v24, v28, v24
	v_mul_f32_e32 v25, v29, v25
	v_mul_f32_e32 v26, v30, v26
	v_mul_f32_e32 v27, v31, v27
	v_mul_f32_e32 v16, v20, v16
	v_mul_f32_e32 v18, v22, v18
	v_mul_f32_e32 v8, v12, v8
	v_mul_f32_e32 v9, v13, v9
	v_mul_f32_e32 v10, v14, v10
	v_mul_f32_e32 v11, v15, v11
	v_mul_f32_e32 v0, v4, v0
	v_mul_f32_e32 v2, v6, v2
	v_readlane_b32 s99, v246, 6
	s_nop 1
	s_cmp_lt_u32 s99, 4
	s_cbranch_scc0 .Lnoal_6
	s_barrier
.Lnoal_6:
	s_waitcnt vmcnt(0)
	v_fmamk_f32 v147, v147, 0x3a800000, v146
	v_fmamk_f32 v148, v150, 0x3a800000, v146
	v_rsq_f32_e32 v150, v148
	v_rsq_f32_e32 v149, v147
	v_mul_f32_e32 v150, 0xbfb8aa3b, v150
	v_mul_f32_e32 v109, v109, v150
	v_exp_f32_e32 v109, v109
	v_mul_f32_e32 v110, v110, v150
	v_exp_f32_e32 v110, v110
	v_mul_f32_e32 v159, v100, v150
	v_fma_f32 v109, v109, v148, v148
	v_rcp_f32_e32 v109, v109
	v_fma_f32 v110, v110, v148, v148
	v_rcp_f32_e32 v110, v110
	v_mul_f32_e32 v149, 0xbfb8aa3b, v149
	v_mul_f32_e32 v105, v105, v109
	v_exp_f32_e32 v109, v159
	v_mul_f32_e32 v106, v106, v110
	v_mul_f32_e32 v110, v101, v150
	v_exp_f32_e32 v110, v110
	v_fma_f32 v109, v109, v148, v148
	v_rcp_f32_e32 v109, v109
	v_mul_f32_e32 v116, v116, v149
	v_mul_f32_e32 v117, v117, v149
	v_mul_f32_e32 v118, v118, v149
	v_mul_f32_e32 v100, v96, v109
	v_mul_f32_e32 v96, v101, v97
	v_fma_f32 v97, v110, v148, v148
	v_mul_f32_e32 v101, v102, v150
	v_rcp_f32_e32 v97, v97
	v_exp_f32_e32 v101, v101
	v_mul_f32_e32 v119, v119, v149
	v_mul_f32_e32 v112, v112, v149
	v_mul_f32_e32 v113, v113, v149
	v_mul_f32_e32 v114, v114, v149
	v_mul_f32_e32 v115, v115, v149
	v_mul_f32_e32 v108, v108, v150
	v_mul_f32_e32 v149, v111, v150
	v_exp_f32_e32 v116, v116
	v_mul_f32_e32 v109, v103, v150
	v_mul_f32_e32 v110, v96, v97
	v_fma_f32 v96, v101, v148, v148
	v_exp_f32_e32 v117, v117
	v_exp_f32_e32 v118, v118
	v_exp_f32_e32 v119, v119
	v_exp_f32_e32 v112, v112
	v_exp_f32_e32 v113, v113
	v_exp_f32_e32 v114, v114
	v_exp_f32_e32 v115, v115
	v_exp_f32_e32 v108, v108
	v_exp_f32_e32 v149, v149
	v_exp_f32_e32 v109, v109
	v_rcp_f32_e32 v96, v96
	v_fma_f32 v116, v116, v147, v147
	v_fmamk_f32 v102, v154, 0x3a800000, v146
	v_fma_f32 v117, v117, v147, v147
	v_fma_f32 v118, v118, v147, v147
	v_fma_f32 v119, v119, v147, v147
	v_fma_f32 v112, v112, v147, v147
	v_fma_f32 v113, v113, v147, v147
	v_fma_f32 v114, v114, v147, v147
	v_fmac_f32_e32 v147, v115, v147
	v_fma_f32 v108, v108, v148, v148
	v_fma_f32 v115, v149, v148, v148
	v_rcp_f32_e32 v116, v116
	v_fmac_f32_e32 v148, v109, v148
	v_mul_f32_e32 v101, v98, v96
	v_mul_f32_e32 v96, v103, v99
	v_rsq_f32_e32 v103, v102
	v_rcp_f32_e32 v117, v117
	v_rcp_f32_e32 v118, v118
	v_rcp_f32_e32 v119, v119
	v_rcp_f32_e32 v112, v112
	v_rcp_f32_e32 v113, v113
	v_rcp_f32_e32 v114, v114
	v_rcp_f32_e32 v147, v147
	v_rcp_f32_e32 v108, v108
	v_rcp_f32_e32 v149, v115
	v_rcp_f32_e32 v97, v148
	v_mul_f32_e32 v115, v124, v116
	v_mul_f32_e32 v103, 0xbfb8aa3b, v103
	v_mul_f32_e32 v116, v125, v117
	v_mul_f32_e32 v117, v126, v118
	v_mul_f32_e32 v118, v127, v119
	v_mul_f32_e32 v119, v151, v112
	v_mul_f32_e32 v124, v152, v113
	v_mul_f32_e32 v122, v122, v114
	v_mul_f32_e32 v123, v123, v147
	v_mul_f32_e32 v108, v153, v108
	v_cvt_pk_bf16_f32 v112, v115, v116
	v_cvt_pk_bf16_f32 v113, v117, v118
	v_cvt_pk_bf16_f32 v114, v119, v124
	v_cvt_pk_bf16_f32 v115, v122, v123
	global_store_dwordx4 v[120:121], v[112:115], off sc1
	v_mul_f32_e32 v107, v107, v149
	v_mul_f32_e32 v99, v96, v97
	v_cvt_pk_bf16_f32 v96, v108, v105
	v_cvt_pk_bf16_f32 v97, v106, v107
	v_mul_f32_e32 v105, v92, v103
	v_mul_f32_e32 v106, v93, v103
	v_mul_f32_e32 v92, v94, v103
	v_mul_f32_e32 v93, v95, v103
	v_exp_f32_e32 v92, v92
	v_exp_f32_e32 v93, v93
	v_mul_f32_e32 v94, v84, v103
; __device__ __forceinline__ unsigned cvt_pk_bf16(float lo, float hi) { unsigned r; asm volatile("v_cvt_pk_bf16_f32 %0, %1, %2" : "=v"(r) : "v"(lo), "v"(hi)); return r; }
;     __device__ __forceinline__ void operator()(f32x4 (&acc)[2][2][4][2], const Unit& u, int wr, int wc, int fr, int fq) const {
;     ...
;             for (int m = 0; m < 4; ++m) { const float ms = sq[ai][m] * (1.0f / 1024.0f) + 1e-6f, nrl = -__builtin_amdgcn_rsqf(ms) * LOG2E;
;                 float o[8];
; #pragma unroll
;                 for (int n = 0; n < 2; ++n)
; #pragma unroll
;                     for (int e = 0; e < 4; ++e) { const float a = acc[ai][0][m][n][e], bb = acc[ai][1][m][n][e];
;                         o[4 * n + e] = (a * bb) * __builtin_amdgcn_rcpf(__builtin_fmaf(__builtin_amdgcn_exp2f(a * nrl), ms, ms)); }
;                 u32x4 w; w.x = cvt_pk_bf16(o[0], o[1]); w.y = cvt_pk_bf16(o[2], o[3]); w.z = cvt_pk_bf16(o[4], o[5]); w.w = cvt_pk_bf16(o[6], o[7]);
;                 *(u32x4*)((char*)Ob + ai * HTB + lds_byte(wr * 64 + m * 16 + fr, (col0 & 63))) = w; }
	v_exp_f32_e32 v94, v94
	v_fma_f32 v92, v92, v102, v102
	v_fma_f32 v93, v93, v102, v102
	v_rcp_f32_e32 v92, v92
	v_rcp_f32_e32 v93, v93
	v_exp_f32_e32 v105, v105
	v_exp_f32_e32 v106, v106
	v_mul_f32_e32 v90, v90, v92
	v_mul_f32_e32 v91, v91, v93
	v_fma_f32 v92, v94, v102, v102
	v_mul_f32_e32 v93, v85, v103
	v_rcp_f32_e32 v92, v92
	v_exp_f32_e32 v93, v93
	v_cvt_pk_bf16_f32 v98, v100, v110
	v_cvt_pk_bf16_f32 v99, v101, v99
	v_mul_f32_e32 v84, v80, v92
	v_mul_f32_e32 v80, v85, v81
	v_fma_f32 v81, v93, v102, v102
	v_mul_f32_e32 v85, v86, v103
	v_rcp_f32_e32 v81, v81
	v_exp_f32_e32 v85, v85
	v_mul_f32_e32 v92, v87, v103
	v_exp_f32_e32 v92, v92
	v_mul_f32_e32 v93, v80, v81
	v_fma_f32 v80, v85, v102, v102
	v_rcp_f32_e32 v80, v80
	v_lshl_add_u64 v[100:101], s[60:61], 0, v[130:131]
	global_store_dwordx4 v[100:101], v[96:99], off sc1
	v_fmamk_f32 v86, v155, 0x3a800000, v146
	v_mul_f32_e32 v85, v82, v80
	v_fma_f32 v96, v105, v102, v102
	v_fma_f32 v97, v106, v102, v102
	v_rcp_f32_e32 v96, v96
	v_rcp_f32_e32 v97, v97
	v_fmac_f32_e32 v102, v92, v102
	v_mul_f32_e32 v80, v87, v83
	v_rsq_f32_e32 v87, v86
	v_rcp_f32_e32 v81, v102
	v_mul_f32_e32 v88, v88, v96
	v_mul_f32_e32 v89, v89, v97
	v_mul_f32_e32 v87, 0xbfb8aa3b, v87
	v_mul_f32_e32 v83, v80, v81
	v_cvt_pk_bf16_f32 v80, v88, v89
	v_mul_f32_e32 v88, v76, v87
	v_mul_f32_e32 v89, v77, v87
	v_mul_f32_e32 v76, v78, v87
	v_mul_f32_e32 v77, v79, v87
	v_exp_f32_e32 v76, v76
	v_exp_f32_e32 v77, v77
	v_mul_f32_e32 v78, v68, v87
	v_exp_f32_e32 v78, v78
	v_fma_f32 v76, v76, v86, v86
	v_fma_f32 v77, v77, v86, v86
	v_rcp_f32_e32 v76, v76
	v_rcp_f32_e32 v77, v77
	v_exp_f32_e32 v88, v88
	v_exp_f32_e32 v89, v89
	v_mul_f32_e32 v74, v74, v76
	v_mul_f32_e32 v75, v75, v77
	v_fma_f32 v76, v78, v86, v86
	v_mul_f32_e32 v77, v69, v87
	v_rcp_f32_e32 v76, v76
	v_exp_f32_e32 v77, v77
	v_cvt_pk_bf16_f32 v81, v90, v91
	v_cvt_pk_bf16_f32 v82, v84, v93
	v_mul_f32_e32 v68, v64, v76
	v_mul_f32_e32 v64, v69, v65
	v_fma_f32 v65, v77, v86, v86
	v_mul_f32_e32 v69, v70, v87
	v_rcp_f32_e32 v65, v65
	v_exp_f32_e32 v69, v69
	v_mul_f32_e32 v76, v71, v87
	v_exp_f32_e32 v76, v76
	v_mul_f32_e32 v77, v64, v65
	v_fma_f32 v64, v69, v86, v86
	v_cvt_pk_bf16_f32 v83, v85, v83
	v_lshl_add_u64 v[84:85], s[60:61], 0, v[132:133]
	v_rcp_f32_e32 v64, v64
	global_store_dwordx4 v[84:85], v[80:83], off sc1
	v_fmamk_f32 v70, v156, 0x3a800000, v146
	v_mul_f32_e32 v69, v66, v64
	v_fma_f32 v80, v88, v86, v86
	v_fma_f32 v81, v89, v86, v86
	v_fmac_f32_e32 v86, v76, v86
	v_rcp_f32_e32 v65, v86
	v_rcp_f32_e32 v80, v80
	v_rcp_f32_e32 v81, v81
	v_mul_f32_e32 v64, v71, v67
	v_rsq_f32_e32 v71, v70
	v_mul_f32_e32 v67, v64, v65
	v_mul_f32_e32 v72, v72, v80
	v_mul_f32_e32 v73, v73, v81
	v_cvt_pk_bf16_f32 v64, v72, v73
	v_cvt_pk_bf16_f32 v65, v74, v75
	v_cvt_pk_bf16_f32 v66, v68, v77
	v_cvt_pk_bf16_f32 v67, v69, v67
	v_lshl_add_u64 v[68:69], s[60:61], 0, v[134:135]
	global_store_dwordx4 v[68:69], v[64:67], off sc1
	s_add_u32 s60, s60, 0x4000
	s_addc_u32 s61, s61, 0
	v_mul_f32_e32 v64, 0xbfb8aa3b, v71
	v_mul_f32_e32 v65, v60, v64
	v_mul_f32_e32 v66, v61, v64
	v_mul_f32_e32 v60, v62, v64
	v_mul_f32_e32 v61, v63, v64
	v_exp_f32_e32 v60, v60
	v_exp_f32_e32 v61, v61
	v_mul_f32_e32 v62, v52, v64
	v_exp_f32_e32 v62, v62
	v_fma_f32 v60, v60, v70, v70
	v_fma_f32 v61, v61, v70, v70
	v_rcp_f32_e32 v60, v60
	v_rcp_f32_e32 v61, v61
	v_exp_f32_e32 v65, v65
	v_exp_f32_e32 v66, v66
	v_mul_f32_e32 v58, v58, v60
	v_mul_f32_e32 v59, v59, v61
	v_fma_f32 v60, v62, v70, v70
	v_mul_f32_e32 v61, v53, v64
	v_rcp_f32_e32 v60, v60
	v_exp_f32_e32 v61, v61
	v_fma_f32 v65, v65, v70, v70
	v_fma_f32 v66, v66, v70, v70
	v_mul_f32_e32 v52, v48, v60
	v_mul_f32_e32 v48, v53, v49
	v_fma_f32 v49, v61, v70, v70
	v_mul_f32_e32 v53, v54, v64
	v_rcp_f32_e32 v49, v49
	v_exp_f32_e32 v53, v53
	v_mul_f32_e32 v60, v55, v64
	v_exp_f32_e32 v60, v60
	v_mul_f32_e32 v61, v48, v49
	v_fma_f32 v48, v53, v70, v70
	v_rcp_f32_e32 v48, v48
	v_fmamk_f32 v54, v157, 0x3a800000, v146
	v_rcp_f32_e32 v65, v65
	v_rcp_f32_e32 v66, v66
	v_fmac_f32_e32 v70, v60, v70
	v_mul_f32_e32 v53, v50, v48
	v_mul_f32_e32 v48, v55, v51
	v_rsq_f32_e32 v55, v54
	v_rcp_f32_e32 v49, v70
	v_mul_f32_e32 v56, v56, v65
	v_mul_f32_e32 v57, v57, v66
	v_mul_f32_e32 v55, 0xbfb8aa3b, v55
	v_mul_f32_e32 v51, v48, v49
	v_cvt_pk_bf16_f32 v48, v56, v57
	v_mul_f32_e32 v56, v44, v55
	v_mul_f32_e32 v57, v45, v55
	v_mul_f32_e32 v44, v46, v55
	v_mul_f32_e32 v45, v47, v55
	v_exp_f32_e32 v44, v44
	v_exp_f32_e32 v45, v45
	v_mul_f32_e32 v46, v36, v55
; __device__ __forceinline__ unsigned cvt_pk_bf16(float lo, float hi) { unsigned r; asm volatile("v_cvt_pk_bf16_f32 %0, %1, %2" : "=v"(r) : "v"(lo), "v"(hi)); return r; }
; #define PG8_BAR __builtin_amdgcn_s_barrier()
;     __device__ __forceinline__ void operator()(f32x4 (&acc)[2][2][4][2], const Unit& u, int wr, int wc, int fr, int fq) const {
;     ...
;             for (int m = 0; m < 4; ++m) { const float ms = sq[ai][m] * (1.0f / 1024.0f) + 1e-6f, nrl = -__builtin_amdgcn_rsqf(ms) * LOG2E;
;                 float o[8];
; #pragma unroll
;                 for (int n = 0; n < 2; ++n)
; #pragma unroll
;                     for (int e = 0; e < 4; ++e) { const float a = acc[ai][0][m][n][e], bb = acc[ai][1][m][n][e];
;                         o[4 * n + e] = (a * bb) * __builtin_amdgcn_rcpf(__builtin_fmaf(__builtin_amdgcn_exp2f(a * nrl), ms, ms)); }
;                 u32x4 w; w.x = cvt_pk_bf16(o[0], o[1]); w.y = cvt_pk_bf16(o[2], o[3]); w.z = cvt_pk_bf16(o[4], o[5]); w.w = cvt_pk_bf16(o[6], o[7]);
;                 *(u32x4*)((char*)Ob + ai * HTB + lds_byte(wr * 64 + m * 16 + fr, (col0 & 63))) = w; }
; template <class Epi, class Sched, bool ALIGN_EPI = false, bool SP2 = false>
; __device__ __forceinline__ void gemm_phase(PG8_LAS unsigned char* lds, const Gemm g, const Sched& S, const Epi& E) {
;     ...
;         if (!has_next) break;
; #pragma unroll
;         for (int a = 0; a < 2; ++a)
; #pragma unroll
;             for (int b = 0; b < 2; ++b)
; #pragma unroll
;                 for (int m = 0; m < 4; ++m)
; #pragma unroll
;                     for (int n = 0; n < 2; ++n) acc[a][b][m][n] = (f32x4){0.f, 0.f, 0.f, 0.f};
;         cur = nxt; cA = nA; cB = nB; ++ui;
;         if constexpr (ALIGN_EPI) { if (wr == 1) PG8_BAR; }
	v_exp_f32_e32 v46, v46
	v_fma_f32 v44, v44, v54, v54
	v_fma_f32 v45, v45, v54, v54
	v_rcp_f32_e32 v44, v44
	v_rcp_f32_e32 v45, v45
	v_exp_f32_e32 v56, v56
	v_exp_f32_e32 v57, v57
	v_mul_f32_e32 v42, v42, v44
	v_mul_f32_e32 v43, v43, v45
	v_fma_f32 v44, v46, v54, v54
	v_mul_f32_e32 v45, v37, v55
	v_rcp_f32_e32 v44, v44
	v_exp_f32_e32 v45, v45
	v_cvt_pk_bf16_f32 v49, v58, v59
	v_cvt_pk_bf16_f32 v50, v52, v61
	v_mul_f32_e32 v36, v32, v44
	v_mul_f32_e32 v32, v37, v33
	v_fma_f32 v33, v45, v54, v54
	v_mul_f32_e32 v37, v38, v55
	v_rcp_f32_e32 v33, v33
	v_exp_f32_e32 v37, v37
	v_mul_f32_e32 v44, v39, v55
	v_exp_f32_e32 v44, v44
	v_mul_f32_e32 v45, v32, v33
	v_fma_f32 v32, v37, v54, v54
	v_rcp_f32_e32 v32, v32
	v_cvt_pk_bf16_f32 v51, v53, v51
	v_lshl_add_u64 v[52:53], s[60:61], 0, v[128:129]
	global_store_dwordx4 v[52:53], v[48:51], off sc1
	v_fmamk_f32 v38, v158, 0x3a800000, v146
	v_mul_f32_e32 v37, v34, v32
	v_fma_f32 v48, v56, v54, v54
	v_fma_f32 v49, v57, v54, v54
	v_rcp_f32_e32 v48, v48
	v_rcp_f32_e32 v49, v49
	v_fmac_f32_e32 v54, v44, v54
	v_mul_f32_e32 v32, v39, v35
	v_rsq_f32_e32 v39, v38
	v_rcp_f32_e32 v33, v54
	v_mul_f32_e32 v40, v40, v48
	v_mul_f32_e32 v41, v41, v49
	v_mul_f32_e32 v39, 0xbfb8aa3b, v39
	v_mul_f32_e32 v35, v32, v33
	v_cvt_pk_bf16_f32 v32, v40, v41
	v_mul_f32_e32 v40, v28, v39
	v_mul_f32_e32 v41, v29, v39
	v_mul_f32_e32 v28, v30, v39
	v_mul_f32_e32 v29, v31, v39
	v_exp_f32_e32 v28, v28
	v_exp_f32_e32 v29, v29
	v_mul_f32_e32 v30, v20, v39
	v_exp_f32_e32 v30, v30
	v_fma_f32 v28, v28, v38, v38
	v_fma_f32 v29, v29, v38, v38
	v_rcp_f32_e32 v28, v28
	v_rcp_f32_e32 v29, v29
	v_exp_f32_e32 v40, v40
	v_exp_f32_e32 v41, v41
	v_mul_f32_e32 v26, v26, v28
	v_mul_f32_e32 v27, v27, v29
	v_fma_f32 v28, v30, v38, v38
	v_mul_f32_e32 v29, v21, v39
	v_rcp_f32_e32 v28, v28
	v_exp_f32_e32 v29, v29
	v_cvt_pk_bf16_f32 v33, v42, v43
	v_cvt_pk_bf16_f32 v34, v36, v45
	v_mul_f32_e32 v20, v16, v28
	v_mul_f32_e32 v16, v21, v17
	v_fma_f32 v17, v29, v38, v38
	v_mul_f32_e32 v21, v22, v39
	v_rcp_f32_e32 v17, v17
	v_exp_f32_e32 v21, v21
	v_mul_f32_e32 v28, v23, v39
	v_exp_f32_e32 v28, v28
	v_mul_f32_e32 v29, v16, v17
	v_fma_f32 v16, v21, v38, v38
	v_rcp_f32_e32 v16, v16
	v_cvt_pk_bf16_f32 v35, v37, v35
	v_lshl_add_u64 v[36:37], s[60:61], 0, v[130:131]
	global_store_dwordx4 v[36:37], v[32:35], off sc1
	v_fmamk_f32 v22, v104, 0x3a800000, v146
	v_mul_f32_e32 v21, v18, v16
	v_fma_f32 v32, v40, v38, v38
	v_fma_f32 v33, v41, v38, v38
	v_rcp_f32_e32 v32, v32
	v_rcp_f32_e32 v33, v33
	v_fmac_f32_e32 v38, v28, v38
	v_mul_f32_e32 v16, v23, v19
	v_rsq_f32_e32 v23, v22
	v_rcp_f32_e32 v17, v38
	v_mul_f32_e32 v24, v24, v32
	v_mul_f32_e32 v25, v25, v33
	v_mul_f32_e32 v23, 0xbfb8aa3b, v23
	v_mul_f32_e32 v19, v16, v17
	v_cvt_pk_bf16_f32 v16, v24, v25
	v_mul_f32_e32 v24, v12, v23
	v_mul_f32_e32 v25, v13, v23
	v_mul_f32_e32 v12, v14, v23
	v_mul_f32_e32 v13, v15, v23
	v_exp_f32_e32 v12, v12
	v_exp_f32_e32 v13, v13
	v_mul_f32_e32 v14, v4, v23
	v_exp_f32_e32 v14, v14
	v_fma_f32 v12, v12, v22, v22
	v_fma_f32 v13, v13, v22, v22
	v_rcp_f32_e32 v12, v12
	v_rcp_f32_e32 v13, v13
	v_exp_f32_e32 v24, v24
	v_exp_f32_e32 v25, v25
	v_mul_f32_e32 v10, v10, v12
	v_mul_f32_e32 v11, v11, v13
	v_fma_f32 v12, v14, v22, v22
	v_mul_f32_e32 v13, v5, v23
	v_rcp_f32_e32 v12, v12
	v_exp_f32_e32 v13, v13
	v_cvt_pk_bf16_f32 v17, v26, v27
	v_cvt_pk_bf16_f32 v18, v20, v29
	v_mul_f32_e32 v4, v0, v12
	v_mul_f32_e32 v0, v5, v1
	v_fma_f32 v1, v13, v22, v22
	v_mul_f32_e32 v5, v6, v23
	v_rcp_f32_e32 v1, v1
	v_exp_f32_e32 v5, v5
	v_mul_f32_e32 v12, v7, v23
	v_exp_f32_e32 v12, v12
	v_cvt_pk_bf16_f32 v19, v21, v19
	v_lshl_add_u64 v[20:21], s[60:61], 0, v[132:133]
	v_mul_f32_e32 v13, v0, v1
	v_fma_f32 v0, v5, v22, v22
	global_store_dwordx4 v[20:21], v[16:19], off sc1
	v_rcp_f32_e32 v0, v0
	s_andn2_b64 vcc, exec, s[2:3]
	v_fma_f32 v16, v24, v22, v22
	v_fma_f32 v17, v25, v22, v22
	v_fmac_f32_e32 v22, v12, v22
	v_rcp_f32_e32 v1, v22
	v_rcp_f32_e32 v16, v16
	v_rcp_f32_e32 v17, v17
	v_mul_f32_e32 v5, v2, v0
	v_mul_f32_e32 v0, v7, v3
	v_mul_f32_e32 v3, v0, v1
	v_mul_f32_e32 v8, v8, v16
	v_mul_f32_e32 v9, v9, v17
	v_cvt_pk_bf16_f32 v0, v8, v9
	v_cvt_pk_bf16_f32 v1, v10, v11
	v_cvt_pk_bf16_f32 v2, v4, v13
	v_cvt_pk_bf16_f32 v3, v5, v3
	v_lshl_add_u64 v[4:5], s[60:61], 0, v[134:135]
	s_mov_b64 s[2:3], -1
	global_store_dwordx4 v[4:5], v[0:3], off sc1
	s_cbranch_vccnz .LBB0_834
	s_andn2_b64 vcc, exec, s[42:43]
	s_cbranch_vccnz .LBB0_833
	s_barrier
	s_branch .LBB0_833

; __device__ __forceinline__ unsigned cvt_pk_bf16(float lo, float hi) { unsigned r; asm volatile("v_cvt_pk_bf16_f32 %0, %1, %2" : "=v"(r) : "v"(lo), "v"(hi)); return r; }
; __device__ __forceinline__ float bf_lo(unsigned w) { return __uint_as_float(w << 16); }
; __device__ __forceinline__ float bf_hi(unsigned w) { return __uint_as_float(w & 0xffff0000u); }
; #define PG8_BAR __builtin_amdgcn_s_barrier()
;     __device__ __forceinline__ void operator()(f32x4 (&acc)[2][2][4][2], const Unit& u, int wr, int wc, int fr, int fq) const {
;     ...
;                 for (int bj = 0; bj < 2; ++bj) pre[ai][m][bj] = *(const u32x4*)hb_at(u, ai, m, bj, wr, wc, fr, fq);
; #pragma unroll
;         for (int ai = 0; ai < 2; ++ai)
; #pragma unroll
;             for (int m = 0; m < 4; ++m) { const int row = row0 + ai * HALF + m * 16; float s = 0.f;
; #pragma unroll
;                 for (int bj = 0; bj < 2; ++bj) { const size_t o2 = (size_t)row * 1024 + col0 + bj * HALF; const u32x4 p = pre[ai][m][bj]; const f32x4 a0 = acc[ai][bj][m][0], a1 = acc[ai][bj][m][1];
;                     f32x4 o0, o1; o0[0] = bf_lo(p.x) + a0[0] * alpha; o0[1] = bf_hi(p.x) + a0[1] * alpha; o0[2] = bf_lo(p.y) + a0[2] * alpha; o0[3] = bf_hi(p.y) + a0[3] * alpha;
;                     o1[0] = bf_lo(p.z) + a1[0] * alpha; o1[1] = bf_hi(p.z) + a1[1] * alpha; o1[2] = bf_lo(p.w) + a1[2] * alpha; o1[3] = bf_hi(p.w) + a1[3] * alpha;
;                     s += ((o0[0] * o0[0] + o0[1] * o0[1]) + (o0[2] * o0[2] + o0[3] * o0[3])) + ((o1[0] * o1[0] + o1[1] * o1[1]) + (o1[2] * o1[2] + o1[3] * o1[3]));
;                     u32x4 w; w.x = cvt_pk_bf16(o0[0], o0[1]); w.y = cvt_pk_bf16(o0[2], o0[3]); w.z = cvt_pk_bf16(o1[0], o1[1]); w.w = cvt_pk_bf16(o1[2], o1[3]);
;                     *(u32x4*)hb_at(u, ai, m, bj, wr, wc, fr, fq) = w;
;                     if (out) { *(f32x4*)(out + o2) = o0; *(f32x4*)(out + o2 + 4) = o1; } }
; template <class Epi, class Sched, bool ALIGN_EPI = false, bool SP2 = false>
; __device__ __forceinline__ void gemm_phase(PG8_LAS unsigned char* lds, const Gemm g, const Sched& S, const Epi& E) {
;     ...
;         if constexpr (ALIGN_EPI) { if (wr == 0) PG8_BAR; }
.LBB0_927:
	s_lshl_b32 s6, s73, 3
	s_lshl_b32 s7, s72, 5
	s_add_i32 s7, s7, s6
	s_or_b32 s6, s7, s77
	s_or_b32 s64, s6, 4
	s_ashr_i32 s7, s6, 31
	s_ashr_i32 s65, s64, 31
	s_lshl_b64 s[68:69], s[6:7], 14
	s_lshl_b64 s[70:71], s[64:65], 14
	v_lshl_add_u64 v[84:85], v[202:203], 0, s[68:69]
	v_lshl_add_u64 v[86:87], v[202:203], 0, s[70:71]
	global_load_dwordx4 v[228:231], v[84:85], off
	global_load_dwordx4 v[184:187], v[86:87], off
	v_lshl_add_u64 v[84:85], v[204:205], 0, s[68:69]
	v_lshl_add_u64 v[86:87], v[204:205], 0, s[70:71]
	s_or_b32 s64, s6, 1
	s_or_b32 s6, s6, 5
	global_load_dwordx4 v[180:183], v[84:85], off
	global_load_dwordx4 v[176:179], v[86:87], off
	v_lshl_add_u64 v[84:85], v[206:207], 0, s[68:69]
	v_lshl_add_u64 v[86:87], v[206:207], 0, s[70:71]
	s_ashr_i32 s65, s64, 31
	s_ashr_i32 s7, s6, 31
	global_load_dwordx4 v[172:175], v[84:85], off
	global_load_dwordx4 v[168:171], v[86:87], off
	v_lshl_add_u64 v[84:85], v[200:201], 0, s[68:69]
	v_lshl_add_u64 v[86:87], v[200:201], 0, s[70:71]
	s_lshl_b64 s[66:67], s[64:65], 14
	s_lshl_b64 s[64:65], s[6:7], 14
	global_load_dwordx4 v[164:167], v[84:85], off
	global_load_dwordx4 v[160:163], v[86:87], off
	v_lshl_add_u64 v[84:85], v[202:203], 0, s[66:67]
	v_lshl_add_u64 v[86:87], v[202:203], 0, s[64:65]
	global_load_dwordx4 v[156:159], v[84:85], off
	global_load_dwordx4 v[152:155], v[86:87], off
	v_lshl_add_u64 v[84:85], v[204:205], 0, s[66:67]
	v_lshl_add_u64 v[86:87], v[204:205], 0, s[64:65]
	global_load_dwordx4 v[140:143], v[84:85], off
	global_load_dwordx4 v[128:131], v[86:87], off
	v_lshl_add_u64 v[84:85], v[206:207], 0, s[66:67]
	v_lshl_add_u64 v[86:87], v[206:207], 0, s[64:65]
	global_load_dwordx4 v[116:119], v[84:85], off
	global_load_dwordx4 v[104:107], v[86:87], off
	v_lshl_add_u64 v[84:85], v[200:201], 0, s[66:67]
	v_lshl_add_u64 v[86:87], v[200:201], 0, s[64:65]
	global_load_dwordx4 v[92:95], v[84:85], off
	s_nop 0
	global_load_dwordx4 v[84:87], v[86:87], off
	v_lshl_add_u32 v214, s72, 8, v219
	v_lshl_or_b32 v212, s73, 8, v220
	v_cndmask_b32_e64 v216, 0, 1, s[56:57]
	v_ashrrev_i32_e32 v215, 31, v214
	v_ashrrev_i32_e32 v213, 31, v212
	v_cmp_ne_u32_e64 s[6:7], 1, v216
	v_lshlrev_b64 v[216:217], 10, v[214:215]
	s_add_u32 s68, s12, s68
	v_lshl_add_u64 v[216:217], v[216:217], 0, v[212:213]
	s_addc_u32 s69, s13, s69
	s_andn2_b64 vcc, exec, s[56:57]
	v_lshl_add_u64 v[232:233], s[68:69], 0, v[194:195]
	v_lshl_add_u64 v[216:217], v[216:217], 2, s[20:21]
	v_readlane_b32 s99, v246, 6
	s_nop 1
	s_cmp_lt_u32 s99, 4
	s_cbranch_scc0 .Lnoal_7
	s_barrier
.Lnoal_7:
	s_waitcnt vmcnt(0)
	v_lshlrev_b32_e32 v234, 16, v228
	v_and_b32_e32 v235, 0xffff0000, v228
	v_lshlrev_b32_e32 v228, 16, v229
	v_and_b32_e32 v229, 0xffff0000, v229
	v_lshlrev_b32_e32 v236, 16, v230
	v_and_b32_e32 v237, 0xffff0000, v230
	v_lshlrev_b32_e32 v230, 16, v231
	v_and_b32_e32 v231, 0xffff0000, v231
	v_pk_fma_f32 v[148:149], v[148:149], 0.5, v[234:235] op_sel_hi:[1,0,1]
	v_pk_fma_f32 v[150:151], v[150:151], 0.5, v[228:229] op_sel_hi:[1,0,1]
	v_pk_fma_f32 v[144:145], v[144:145], 0.5, v[236:237] op_sel_hi:[1,0,1]
	v_pk_fma_f32 v[146:147], v[146:147], 0.5, v[230:231] op_sel_hi:[1,0,1]
	v_cvt_pk_bf16_f32 v228, v148, v149
	v_cvt_pk_bf16_f32 v229, v150, v151
	v_cvt_pk_bf16_f32 v230, v144, v145
	s_nop 0
	v_cvt_pk_bf16_f32 v231, v146, v147
	global_store_dwordx4 v[232:233], v[228:231], off
	s_cbranch_vccnz .LBB0_929
	global_store_dwordx4 v[216:217], v[148:151], off
	global_store_dwordx4 v[216:217], v[144:147], off offset:16
